# f30 + sigmoid gates kept in a tile-private layout (tile, row block, thread): the gate GEMM epilogue writes both column halves of a row block as one 16-B store, the P3 chain reads them back as 16-B loa
# speedup vs baseline: 1.0139x; 1.0104x over previous
; __device__ __forceinline__ float sigmoidf_(float x) { return frcp(1.0f + fexp(-x)); }
;     __device__ __forceinline__ void operator()(const Acc& acc, const Unit& u, int wr, int wc, int fr, int fq) const {
;     ...
; #pragma unroll
;         for (int ai = 0; ai < 2; ++ai)
; #pragma unroll
;             for (int m = 0; m < 4; ++m) { const int row = row0 + ai * HALF + m * 16; const float rs = rsv[ai][m]; unsigned char* rowp = GT + (size_t)row * NGT + colt;
; #pragma unroll
;                 for (int bj = 0; bj < 2; ++bj) { f32x4 v0 = acc[ai][bj][m][0] * rs + bv[bj][0], v1 = acc[ai][bj][m][1] * rs + bv[bj][1];
;                     unsigned q0[4], q1[4];
; #pragma unroll
;                     for (int e = 0; e < 4; ++e) { q0[e] = (unsigned)fmaxf(sigmoidf_(v0[e]) * 255.0f + 0.5f, 1.0f); q1[e] = (unsigned)fmaxf(sigmoidf_(v1[e]) * 255.0f + 0.5f, 1.0f); }
;                     u32x2 w; w.x = q0[0] | (q0[1] << 8) | (q0[2] << 16) | (q0[3] << 24); w.y = q1[0] | (q1[1] << 8) | (q1[2] << 16) | (q1[3] << 24);
;                     *(u32x2*)(rowp + bj * HALF) = w; } }
; template <class Epi, class Sched, bool ALIGN_EPI, bool SP2>
; __device__ __forceinline__ void gemm_phase8(LAS unsigned char* lds, const int K, const Sched& S, const Epi& E) {
;     ...
;         asm volatile("s_nop 15\n\ts_nop 7" ::: "memory");
.LBB0_570:
	s_nop 15
	s_nop 7
	s_mul_i32 s99, s42, 24
	s_add_i32 s99, s99, s0
	s_lshl_b32 s99, s99, 16
	v_lshl_add_u32 v222, v0, 4, s99
	v_lshl_add_u32 v24, s42, 8, v193
	s_lshl_b32 s1, s0, 8
	v_or_b32_e32 v22, 16, v24
	v_or_b32_e32 v20, 32, v24
	v_or_b32_e32 v18, 48, v24
	s_mov_b64 s[42:43], -1
	s_cmp_lt_i32 s0, 24
	v_ashrrev_i32_e32 v25, 31, v24
	v_add_u32_e32 v183, 0x80, v24
	v_add_u32_e32 v182, 0x90, v24
	v_add_u32_e32 v181, 0xa0, v24
	v_add_u32_e32 v180, 0xb0, v24
	v_ashrrev_i32_e32 v23, 31, v22
	v_ashrrev_i32_e32 v21, 31, v20
	v_ashrrev_i32_e32 v19, 31, v18
	s_cbranch_scc0 .LBB0_573
	v_or_b32_e32 v26, s1, v189
	v_ashrrev_i32_e32 v27, 31, v26
	v_mov_b64_e32 v[28:29], s[88:89]
	v_mad_i64_i32 v[30:31], s[42:43], v24, s62, v[28:29]
	v_lshl_add_u64 v[186:187], v[30:31], 0, v[26:27]
	s_mov_b32 s98, 0x3b808081
	v_mul_f32_e32 v2, 0xbfb8aa3b, v242
	v_mul_f32_e32 v3, 0xbfb8aa3b, v243
	v_mul_f32_e32 v4, 0xbfb8aa3b, v244
	v_mul_f32_e32 v5, 0xbfb8aa3b, v245
	v_mul_f32_e32 v6, 0xbfb8aa3b, v238
	v_mul_f32_e32 v7, 0xbfb8aa3b, v239
	v_mul_f32_e32 v8, 0xbfb8aa3b, v240
	v_mul_f32_e32 v9, 0xbfb8aa3b, v241
	v_mul_f32_e32 v10, 0xbfb8aa3b, v234
	v_mul_f32_e32 v11, 0xbfb8aa3b, v235
	v_mul_f32_e32 v12, 0xbfb8aa3b, v236
	v_mul_f32_e32 v13, 0xbfb8aa3b, v237
	v_mul_f32_e32 v14, 0xbfb8aa3b, v230
	v_mul_f32_e32 v15, 0xbfb8aa3b, v231
	v_mul_f32_e32 v16, 0xbfb8aa3b, v232
	v_mul_f32_e32 v17, 0xbfb8aa3b, v233
	v_mul_f32_e32 v30, 0xbb38aa3b, v170
	v_mul_f32_e32 v199, 0xbb38aa3b, v246
	v_mul_f32_e32 v200, 0xbb38aa3b, v247
	v_mul_f32_e32 v184, 0xbb38aa3b, v248
	v_mul_f32_e32 v170, 0xbb38aa3b, v249
	v_mul_f32_e32 v33, 0xbb38aa3b, v250
	v_mul_f32_e32 v32, 0xbb38aa3b, v251
	v_mul_f32_e32 v31, 0xbb38aa3b, v195
	v_fma_f32 v202, v158, v199, v14
	v_fma_f32 v203, v154, v199, v10
	v_fma_f32 v204, v159, v199, v15
	v_fma_f32 v205, v155, v199, v11
	v_fma_f32 v206, v160, v199, v16
	v_fma_f32 v207, v156, v199, v12
	v_fma_f32 v208, v161, v199, v17
	v_fma_f32 v209, v157, v199, v13
	v_exp_f32_e32 v202, v202
	v_exp_f32_e32 v203, v203
	v_exp_f32_e32 v204, v204
	v_exp_f32_e32 v205, v205
	v_exp_f32_e32 v206, v206
	v_exp_f32_e32 v207, v207
	v_exp_f32_e32 v208, v208
	v_exp_f32_e32 v209, v209
	s_nop 0
	v_fma_f32 v202, v202, s98, s98 clamp
	v_fma_f32 v203, v203, s98, s98 clamp
	v_fma_f32 v204, v204, s98, s98 clamp
	v_fma_f32 v205, v205, s98, s98 clamp
	v_fma_f32 v206, v206, s98, s98 clamp
	v_fma_f32 v207, v207, s98, s98 clamp
	v_fma_f32 v208, v208, s98, s98 clamp
	v_fma_f32 v209, v209, s98, s98 clamp
	v_rcp_f32_e32 v202, v202
	v_rcp_f32_e32 v203, v203
	v_rcp_f32_e32 v204, v204
	v_rcp_f32_e32 v205, v205
	v_rcp_f32_e32 v206, v206
	v_rcp_f32_e32 v207, v207
	v_rcp_f32_e32 v208, v208
	v_rcp_f32_e32 v209, v209
	s_nop 0
	v_cvt_pk_u8_f32 v210, v202, 0, 0
	v_cvt_pk_u8_f32 v210, v204, 1, v210
	v_cvt_pk_u8_f32 v210, v206, 2, v210
	v_cvt_pk_u8_f32 v210, v208, 3, v210
	v_cvt_pk_u8_f32 v211, v203, 0, 0
	v_cvt_pk_u8_f32 v211, v205, 1, v211
	v_cvt_pk_u8_f32 v211, v207, 2, v211
	v_cvt_pk_u8_f32 v211, v209, 3, v211
	v_fma_f32 v202, v150, v199, v6
	v_fma_f32 v203, v146, v199, v2
	v_fma_f32 v204, v151, v199, v7
	v_fma_f32 v205, v147, v199, v3
	v_fma_f32 v206, v152, v199, v8
	v_fma_f32 v207, v148, v199, v4
	v_fma_f32 v208, v153, v199, v9
	v_fma_f32 v209, v149, v199, v5
	v_exp_f32_e32 v202, v202
	v_exp_f32_e32 v203, v203
	v_exp_f32_e32 v204, v204
	v_exp_f32_e32 v205, v205
	v_exp_f32_e32 v206, v206
	v_exp_f32_e32 v207, v207
	v_exp_f32_e32 v208, v208
	v_exp_f32_e32 v209, v209
	s_nop 0
	v_fma_f32 v202, v202, s98, s98 clamp
	v_fma_f32 v203, v203, s98, s98 clamp
	v_fma_f32 v204, v204, s98, s98 clamp
	v_fma_f32 v205, v205, s98, s98 clamp
	v_fma_f32 v206, v206, s98, s98 clamp
	v_fma_f32 v207, v207, s98, s98 clamp
	v_fma_f32 v208, v208, s98, s98 clamp
	v_fma_f32 v209, v209, s98, s98 clamp
	v_rcp_f32_e32 v202, v202
	v_rcp_f32_e32 v203, v203
	v_rcp_f32_e32 v204, v204
	v_rcp_f32_e32 v205, v205
	v_rcp_f32_e32 v206, v206
	v_rcp_f32_e32 v207, v207
	v_rcp_f32_e32 v208, v208
	v_rcp_f32_e32 v209, v209
	s_nop 0
	v_cvt_pk_u8_f32 v212, v202, 0, 0
	v_cvt_pk_u8_f32 v212, v204, 1, v212
	v_cvt_pk_u8_f32 v212, v206, 2, v212
	v_cvt_pk_u8_f32 v212, v208, 3, v212
	v_cvt_pk_u8_f32 v213, v203, 0, 0
	v_cvt_pk_u8_f32 v213, v205, 1, v213
	v_cvt_pk_u8_f32 v213, v207, 2, v213
	v_cvt_pk_u8_f32 v213, v209, 3, v213
	global_store_dwordx4 v222, v[210:213], s[88:89]
	v_fma_f32 v202, v142, v200, v14
	v_fma_f32 v203, v143, v200, v15
	v_fma_f32 v204, v138, v200, v10
	v_fma_f32 v205, v139, v200, v11
	v_fma_f32 v206, v144, v200, v16
	v_fma_f32 v207, v145, v200, v17
	v_fma_f32 v208, v140, v200, v12
	v_fma_f32 v209, v141, v200, v13
	v_exp_f32_e32 v202, v202
	v_exp_f32_e32 v203, v203
	v_exp_f32_e32 v204, v204
	v_exp_f32_e32 v205, v205
	v_exp_f32_e32 v206, v206
	v_exp_f32_e32 v207, v207
	v_exp_f32_e32 v208, v208
	v_exp_f32_e32 v209, v209
	s_nop 0
	v_fma_f32 v202, v202, s98, s98 clamp
	v_fma_f32 v203, v203, s98, s98 clamp
	v_fma_f32 v204, v204, s98, s98 clamp
	v_fma_f32 v205, v205, s98, s98 clamp
	v_fma_f32 v206, v206, s98, s98 clamp
	v_fma_f32 v207, v207, s98, s98 clamp
	v_fma_f32 v208, v208, s98, s98 clamp
	v_fma_f32 v209, v209, s98, s98 clamp
	v_rcp_f32_e32 v202, v202
	v_rcp_f32_e32 v203, v203
	v_rcp_f32_e32 v204, v204
	v_rcp_f32_e32 v205, v205
	v_rcp_f32_e32 v206, v206
	v_rcp_f32_e32 v207, v207
	v_rcp_f32_e32 v208, v208
	v_rcp_f32_e32 v209, v209
	s_nop 0
	v_cvt_pk_u8_f32 v214, v202, 0, 0
	v_cvt_pk_u8_f32 v214, v203, 1, v214
	v_cvt_pk_u8_f32 v214, v206, 2, v214
	v_cvt_pk_u8_f32 v214, v207, 3, v214
	v_cvt_pk_u8_f32 v215, v204, 0, 0
	v_cvt_pk_u8_f32 v215, v205, 1, v215
	v_cvt_pk_u8_f32 v215, v208, 2, v215
	v_cvt_pk_u8_f32 v215, v209, 3, v215
; __device__ __forceinline__ float sigmoidf_(float x) { return frcp(1.0f + fexp(-x)); }
;     __device__ __forceinline__ void operator()(const Acc& acc, const Unit& u, int wr, int wc, int fr, int fq) const {
;     ...
;             for (int m = 0; m < 4; ++m) { const int row = row0 + ai * HALF + m * 16; const float rs = rsv[ai][m]; unsigned char* rowp = GT + (size_t)row * NGT + colt;
; #pragma unroll
;                 for (int bj = 0; bj < 2; ++bj) { f32x4 v0 = acc[ai][bj][m][0] * rs + bv[bj][0], v1 = acc[ai][bj][m][1] * rs + bv[bj][1];
;                     unsigned q0[4], q1[4];
; #pragma unroll
;                     for (int e = 0; e < 4; ++e) { q0[e] = (unsigned)fmaxf(sigmoidf_(v0[e]) * 255.0f + 0.5f, 1.0f); q1[e] = (unsigned)fmaxf(sigmoidf_(v1[e]) * 255.0f + 0.5f, 1.0f); }
;                     u32x2 w; w.x = q0[0] | (q0[1] << 8) | (q0[2] << 16) | (q0[3] << 24); w.y = q1[0] | (q1[1] << 8) | (q1[2] << 16) | (q1[3] << 24);
;                     *(u32x2*)(rowp + bj * HALF) = w; } }
	v_mad_i64_i32 v[186:187], s[42:43], v22, s62, v[28:29]
	v_lshl_add_u64 v[186:187], v[186:187], 0, v[26:27]
	v_fma_f32 v202, v134, v200, v6
	v_fma_f32 v203, v135, v200, v7
	v_fma_f32 v204, v130, v200, v2
	v_fma_f32 v205, v131, v200, v3
	v_fma_f32 v206, v136, v200, v8
	v_fma_f32 v207, v137, v200, v9
	v_fma_f32 v208, v132, v200, v4
	v_fma_f32 v209, v133, v200, v5
	v_exp_f32_e32 v202, v202
	v_exp_f32_e32 v203, v203
	v_exp_f32_e32 v204, v204
	v_exp_f32_e32 v205, v205
	v_exp_f32_e32 v206, v206
	v_exp_f32_e32 v207, v207
	v_exp_f32_e32 v208, v208
	v_exp_f32_e32 v209, v209
	s_nop 0
	v_fma_f32 v202, v202, s98, s98 clamp
	v_fma_f32 v203, v203, s98, s98 clamp
	v_fma_f32 v204, v204, s98, s98 clamp
	v_fma_f32 v205, v205, s98, s98 clamp
	v_fma_f32 v206, v206, s98, s98 clamp
	v_fma_f32 v207, v207, s98, s98 clamp
	v_fma_f32 v208, v208, s98, s98 clamp
	v_fma_f32 v209, v209, s98, s98 clamp
	v_rcp_f32_e32 v202, v202
	v_rcp_f32_e32 v203, v203
	v_rcp_f32_e32 v204, v204
	v_rcp_f32_e32 v205, v205
	v_rcp_f32_e32 v206, v206
	v_rcp_f32_e32 v207, v207
	v_rcp_f32_e32 v208, v208
	v_rcp_f32_e32 v209, v209
	s_nop 0
	v_cvt_pk_u8_f32 v216, v202, 0, 0
	v_cvt_pk_u8_f32 v216, v203, 1, v216
	v_cvt_pk_u8_f32 v216, v206, 2, v216
	v_cvt_pk_u8_f32 v216, v207, 3, v216
	v_cvt_pk_u8_f32 v217, v204, 0, 0
	v_cvt_pk_u8_f32 v217, v205, 1, v217
	v_cvt_pk_u8_f32 v217, v208, 2, v217
	v_cvt_pk_u8_f32 v217, v209, 3, v217
	v_add_u32_e32 v223, 0x2000, v222
	global_store_dwordx4 v223, v[214:217], s[88:89]
	v_fma_f32 v202, v126, v184, v14
	v_fma_f32 v203, v127, v184, v15
	v_fma_f32 v204, v122, v184, v10
	v_fma_f32 v205, v123, v184, v11
	v_fma_f32 v206, v128, v184, v16
	v_fma_f32 v207, v129, v184, v17
	v_fma_f32 v208, v124, v184, v12
	v_fma_f32 v209, v125, v184, v13
	v_exp_f32_e32 v202, v202
	v_exp_f32_e32 v203, v203
	v_exp_f32_e32 v204, v204
	v_exp_f32_e32 v205, v205
	v_exp_f32_e32 v206, v206
	v_exp_f32_e32 v207, v207
	v_exp_f32_e32 v208, v208
	v_exp_f32_e32 v209, v209
	s_nop 0
	v_fma_f32 v202, v202, s98, s98 clamp
	v_fma_f32 v203, v203, s98, s98 clamp
	v_fma_f32 v204, v204, s98, s98 clamp
	v_fma_f32 v205, v205, s98, s98 clamp
	v_fma_f32 v206, v206, s98, s98 clamp
	v_fma_f32 v207, v207, s98, s98 clamp
	v_fma_f32 v208, v208, s98, s98 clamp
	v_fma_f32 v209, v209, s98, s98 clamp
	v_rcp_f32_e32 v202, v202
	v_rcp_f32_e32 v203, v203
	v_rcp_f32_e32 v204, v204
	v_rcp_f32_e32 v205, v205
	v_rcp_f32_e32 v206, v206
	v_rcp_f32_e32 v207, v207
	v_rcp_f32_e32 v208, v208
	v_rcp_f32_e32 v209, v209
	s_nop 0
	v_cvt_pk_u8_f32 v218, v202, 0, 0
	v_cvt_pk_u8_f32 v218, v203, 1, v218
	v_cvt_pk_u8_f32 v218, v206, 2, v218
	v_cvt_pk_u8_f32 v218, v207, 3, v218
	v_cvt_pk_u8_f32 v219, v204, 0, 0
	v_cvt_pk_u8_f32 v219, v205, 1, v219
	v_cvt_pk_u8_f32 v219, v208, 2, v219
	v_cvt_pk_u8_f32 v219, v209, 3, v219
	v_mad_i64_i32 v[186:187], s[42:43], v20, s62, v[28:29]
	v_lshl_add_u64 v[186:187], v[186:187], 0, v[26:27]
	v_fma_f32 v202, v118, v184, v6
	v_fma_f32 v203, v114, v184, v2
	v_fma_f32 v204, v119, v184, v7
	v_fma_f32 v205, v115, v184, v3
	v_fma_f32 v206, v120, v184, v8
	v_fma_f32 v207, v116, v184, v4
	v_fma_f32 v208, v121, v184, v9
	v_fma_f32 v209, v117, v184, v5
	v_exp_f32_e32 v202, v202
	v_exp_f32_e32 v203, v203
	v_exp_f32_e32 v204, v204
	v_exp_f32_e32 v205, v205
	v_exp_f32_e32 v206, v206
	v_exp_f32_e32 v207, v207
	v_exp_f32_e32 v208, v208
	v_exp_f32_e32 v209, v209
	s_nop 0
	v_fma_f32 v202, v202, s98, s98 clamp
	v_fma_f32 v203, v203, s98, s98 clamp
	v_fma_f32 v204, v204, s98, s98 clamp
	v_fma_f32 v205, v205, s98, s98 clamp
	v_fma_f32 v206, v206, s98, s98 clamp
	v_fma_f32 v207, v207, s98, s98 clamp
	v_fma_f32 v208, v208, s98, s98 clamp
	v_fma_f32 v209, v209, s98, s98 clamp
	v_rcp_f32_e32 v202, v202
	v_rcp_f32_e32 v203, v203
	v_rcp_f32_e32 v204, v204
	v_rcp_f32_e32 v205, v205
	v_rcp_f32_e32 v206, v206
	v_rcp_f32_e32 v207, v207
	v_rcp_f32_e32 v208, v208
	v_rcp_f32_e32 v209, v209
	s_nop 0
	v_cvt_pk_u8_f32 v220, v202, 0, 0
	v_cvt_pk_u8_f32 v220, v204, 1, v220
	v_cvt_pk_u8_f32 v220, v206, 2, v220
	v_cvt_pk_u8_f32 v220, v208, 3, v220
	v_cvt_pk_u8_f32 v221, v203, 0, 0
	v_cvt_pk_u8_f32 v221, v205, 1, v221
	v_cvt_pk_u8_f32 v221, v207, 2, v221
	v_cvt_pk_u8_f32 v221, v209, 3, v221
	v_add_u32_e32 v223, 0x4000, v222
	global_store_dwordx4 v223, v[218:221], s[88:89]
	v_fma_f32 v202, v106, v170, v10
	v_fma_f32 v203, v107, v170, v11
	v_fma_f32 v204, v110, v170, v14
	v_fma_f32 v205, v111, v170, v15
	v_fma_f32 v206, v112, v170, v16
	v_fma_f32 v207, v108, v170, v12
	v_fma_f32 v208, v113, v170, v17
	v_fma_f32 v209, v109, v170, v13
	v_exp_f32_e32 v202, v202
	v_exp_f32_e32 v203, v203
	v_exp_f32_e32 v204, v204
	v_exp_f32_e32 v205, v205
	v_exp_f32_e32 v206, v206
	v_exp_f32_e32 v207, v207
	v_exp_f32_e32 v208, v208
	v_exp_f32_e32 v209, v209
	s_nop 0
	v_fma_f32 v202, v202, s98, s98 clamp
	v_fma_f32 v203, v203, s98, s98 clamp
	v_fma_f32 v204, v204, s98, s98 clamp
	v_fma_f32 v205, v205, s98, s98 clamp
	v_fma_f32 v206, v206, s98, s98 clamp
	v_fma_f32 v207, v207, s98, s98 clamp
	v_fma_f32 v208, v208, s98, s98 clamp
	v_fma_f32 v209, v209, s98, s98 clamp
	v_rcp_f32_e32 v202, v202
	v_rcp_f32_e32 v203, v203
	v_rcp_f32_e32 v204, v204
	v_rcp_f32_e32 v205, v205
	v_rcp_f32_e32 v206, v206
	v_rcp_f32_e32 v207, v207
	v_rcp_f32_e32 v208, v208
	v_rcp_f32_e32 v209, v209
	s_nop 0
	v_cvt_pk_u8_f32 v210, v204, 0, 0
	v_cvt_pk_u8_f32 v210, v205, 1, v210
	v_cvt_pk_u8_f32 v210, v206, 2, v210
	v_cvt_pk_u8_f32 v210, v208, 3, v210
	v_cvt_pk_u8_f32 v211, v202, 0, 0
	v_cvt_pk_u8_f32 v211, v203, 1, v211
	v_cvt_pk_u8_f32 v211, v207, 2, v211
	v_cvt_pk_u8_f32 v211, v209, 3, v211
	v_mad_i64_i32 v[184:185], s[42:43], v18, s62, v[28:29]
	v_lshl_add_u64 v[184:185], v[184:185], 0, v[26:27]
; __device__ __forceinline__ float sigmoidf_(float x) { return frcp(1.0f + fexp(-x)); }
;     __device__ __forceinline__ void operator()(const Acc& acc, const Unit& u, int wr, int wc, int fr, int fq) const {
;     ...
;             for (int m = 0; m < 4; ++m) { const int row = row0 + ai * HALF + m * 16; const float rs = rsv[ai][m]; unsigned char* rowp = GT + (size_t)row * NGT + colt;
; #pragma unroll
;                 for (int bj = 0; bj < 2; ++bj) { f32x4 v0 = acc[ai][bj][m][0] * rs + bv[bj][0], v1 = acc[ai][bj][m][1] * rs + bv[bj][1];
;                     unsigned q0[4], q1[4];
; #pragma unroll
;                     for (int e = 0; e < 4; ++e) { q0[e] = (unsigned)fmaxf(sigmoidf_(v0[e]) * 255.0f + 0.5f, 1.0f); q1[e] = (unsigned)fmaxf(sigmoidf_(v1[e]) * 255.0f + 0.5f, 1.0f); }
;                     u32x2 w; w.x = q0[0] | (q0[1] << 8) | (q0[2] << 16) | (q0[3] << 24); w.y = q1[0] | (q1[1] << 8) | (q1[2] << 16) | (q1[3] << 24);
;                     *(u32x2*)(rowp + bj * HALF) = w; } }
	v_fma_f32 v202, v98, v170, v2
	v_fma_f32 v203, v99, v170, v3
	v_fma_f32 v204, v102, v170, v6
	v_fma_f32 v205, v100, v170, v4
	v_fma_f32 v206, v103, v170, v7
	v_fma_f32 v207, v104, v170, v8
	v_fma_f32 v208, v105, v170, v9
	v_fma_f32 v209, v101, v170, v5
	v_exp_f32_e32 v202, v202
	v_exp_f32_e32 v203, v203
	v_exp_f32_e32 v204, v204
	v_exp_f32_e32 v205, v205
	v_exp_f32_e32 v206, v206
	v_exp_f32_e32 v207, v207
	v_exp_f32_e32 v208, v208
	v_exp_f32_e32 v209, v209
	s_nop 0
	v_fma_f32 v202, v202, s98, s98 clamp
	v_fma_f32 v203, v203, s98, s98 clamp
	v_fma_f32 v204, v204, s98, s98 clamp
	v_fma_f32 v205, v205, s98, s98 clamp
	v_fma_f32 v206, v206, s98, s98 clamp
	v_fma_f32 v207, v207, s98, s98 clamp
	v_fma_f32 v208, v208, s98, s98 clamp
	v_fma_f32 v209, v209, s98, s98 clamp
	v_rcp_f32_e32 v202, v202
	v_rcp_f32_e32 v203, v203
	v_rcp_f32_e32 v204, v204
	v_rcp_f32_e32 v205, v205
	v_rcp_f32_e32 v206, v206
	v_rcp_f32_e32 v207, v207
	v_rcp_f32_e32 v208, v208
	v_rcp_f32_e32 v209, v209
	s_nop 0
	v_cvt_pk_u8_f32 v212, v204, 0, 0
	v_cvt_pk_u8_f32 v212, v206, 1, v212
	v_cvt_pk_u8_f32 v212, v207, 2, v212
	v_cvt_pk_u8_f32 v212, v208, 3, v212
	v_cvt_pk_u8_f32 v213, v202, 0, 0
	v_cvt_pk_u8_f32 v213, v203, 1, v213
	v_cvt_pk_u8_f32 v213, v205, 2, v213
	v_cvt_pk_u8_f32 v213, v209, 3, v213
	v_add_u32_e32 v223, 0x6000, v222
	global_store_dwordx4 v223, v[210:213], s[88:89]
	v_fma_f32 v202, v90, v33, v10
	v_fma_f32 v203, v91, v33, v11
	v_fma_f32 v204, v92, v33, v12
	v_fma_f32 v205, v94, v33, v14
	v_fma_f32 v206, v95, v33, v15
	v_fma_f32 v207, v96, v33, v16
	v_fma_f32 v208, v97, v33, v17
	v_fma_f32 v209, v93, v33, v13
	v_exp_f32_e32 v202, v202
	v_exp_f32_e32 v203, v203
	v_exp_f32_e32 v204, v204
	v_exp_f32_e32 v205, v205
	v_exp_f32_e32 v206, v206
	v_exp_f32_e32 v207, v207
	v_exp_f32_e32 v208, v208
	v_exp_f32_e32 v209, v209
	s_nop 0
	v_fma_f32 v202, v202, s98, s98 clamp
	v_fma_f32 v203, v203, s98, s98 clamp
	v_fma_f32 v204, v204, s98, s98 clamp
	v_fma_f32 v205, v205, s98, s98 clamp
	v_fma_f32 v206, v206, s98, s98 clamp
	v_fma_f32 v207, v207, s98, s98 clamp
	v_fma_f32 v208, v208, s98, s98 clamp
	v_fma_f32 v209, v209, s98, s98 clamp
	v_rcp_f32_e32 v202, v202
	v_rcp_f32_e32 v203, v203
	v_rcp_f32_e32 v204, v204
	v_rcp_f32_e32 v205, v205
	v_rcp_f32_e32 v206, v206
	v_rcp_f32_e32 v207, v207
	v_rcp_f32_e32 v208, v208
	v_rcp_f32_e32 v209, v209
	s_nop 0
	v_cvt_pk_u8_f32 v214, v205, 0, 0
	v_cvt_pk_u8_f32 v214, v206, 1, v214
	v_cvt_pk_u8_f32 v214, v207, 2, v214
	v_cvt_pk_u8_f32 v214, v208, 3, v214
	v_cvt_pk_u8_f32 v215, v202, 0, 0
	v_cvt_pk_u8_f32 v215, v203, 1, v215
	v_cvt_pk_u8_f32 v215, v204, 2, v215
	v_cvt_pk_u8_f32 v215, v209, 3, v215
	v_mad_i64_i32 v[184:185], s[42:43], v183, s62, v[28:29]
	v_lshl_add_u64 v[184:185], v[184:185], 0, v[26:27]
	v_fma_f32 v202, v82, v33, v2
	v_fma_f32 v203, v83, v33, v3
	v_fma_f32 v204, v84, v33, v4
	v_fma_f32 v205, v86, v33, v6
	v_fma_f32 v206, v87, v33, v7
	v_fma_f32 v207, v88, v33, v8
	v_fma_f32 v208, v89, v33, v9
	v_fma_f32 v209, v85, v33, v5
	v_exp_f32_e32 v202, v202
	v_exp_f32_e32 v203, v203
	v_exp_f32_e32 v204, v204
	v_exp_f32_e32 v205, v205
	v_exp_f32_e32 v206, v206
	v_exp_f32_e32 v207, v207
	v_exp_f32_e32 v208, v208
	v_exp_f32_e32 v209, v209
	s_nop 0
	v_fma_f32 v202, v202, s98, s98 clamp
	v_fma_f32 v203, v203, s98, s98 clamp
	v_fma_f32 v204, v204, s98, s98 clamp
	v_fma_f32 v205, v205, s98, s98 clamp
	v_fma_f32 v206, v206, s98, s98 clamp
	v_fma_f32 v207, v207, s98, s98 clamp
	v_fma_f32 v208, v208, s98, s98 clamp
	v_fma_f32 v209, v209, s98, s98 clamp
	v_rcp_f32_e32 v202, v202
	v_rcp_f32_e32 v203, v203
	v_rcp_f32_e32 v204, v204
	v_rcp_f32_e32 v205, v205
	v_rcp_f32_e32 v206, v206
	v_rcp_f32_e32 v207, v207
	v_rcp_f32_e32 v208, v208
	v_rcp_f32_e32 v209, v209
	s_nop 0
	v_cvt_pk_u8_f32 v216, v205, 0, 0
	v_cvt_pk_u8_f32 v216, v206, 1, v216
	v_cvt_pk_u8_f32 v216, v207, 2, v216
	v_cvt_pk_u8_f32 v216, v208, 3, v216
	v_cvt_pk_u8_f32 v217, v202, 0, 0
	v_cvt_pk_u8_f32 v217, v203, 1, v217
	v_cvt_pk_u8_f32 v217, v204, 2, v217
	v_cvt_pk_u8_f32 v217, v209, 3, v217
	v_add_u32_e32 v223, 0x8000, v222
	global_store_dwordx4 v223, v[214:217], s[88:89]
	v_fma_f32 v202, v78, v32, v14
	v_fma_f32 v203, v79, v32, v15
	v_fma_f32 v204, v74, v32, v10
	v_fma_f32 v205, v75, v32, v11
	v_fma_f32 v206, v80, v32, v16
	v_fma_f32 v207, v81, v32, v17
	v_fma_f32 v208, v76, v32, v12
	v_fma_f32 v209, v77, v32, v13
	v_exp_f32_e32 v202, v202
	v_exp_f32_e32 v203, v203
	v_exp_f32_e32 v204, v204
	v_exp_f32_e32 v205, v205
	v_exp_f32_e32 v206, v206
	v_exp_f32_e32 v207, v207
	v_exp_f32_e32 v208, v208
	v_exp_f32_e32 v209, v209
	s_nop 0
	v_fma_f32 v202, v202, s98, s98 clamp
	v_fma_f32 v203, v203, s98, s98 clamp
	v_fma_f32 v204, v204, s98, s98 clamp
	v_fma_f32 v205, v205, s98, s98 clamp
	v_fma_f32 v206, v206, s98, s98 clamp
	v_fma_f32 v207, v207, s98, s98 clamp
	v_fma_f32 v208, v208, s98, s98 clamp
	v_fma_f32 v209, v209, s98, s98 clamp
	v_rcp_f32_e32 v202, v202
	v_rcp_f32_e32 v203, v203
	v_rcp_f32_e32 v204, v204
	v_rcp_f32_e32 v205, v205
	v_rcp_f32_e32 v206, v206
	v_rcp_f32_e32 v207, v207
	v_rcp_f32_e32 v208, v208
	v_rcp_f32_e32 v209, v209
	s_nop 0
	v_cvt_pk_u8_f32 v218, v202, 0, 0
	v_cvt_pk_u8_f32 v218, v203, 1, v218
	v_cvt_pk_u8_f32 v218, v206, 2, v218
	v_cvt_pk_u8_f32 v218, v207, 3, v218
	v_cvt_pk_u8_f32 v219, v204, 0, 0
	v_cvt_pk_u8_f32 v219, v205, 1, v219
	v_cvt_pk_u8_f32 v219, v208, 2, v219
	v_cvt_pk_u8_f32 v219, v209, 3, v219
	v_mad_i64_i32 v[184:185], s[42:43], v182, s62, v[28:29]
	v_lshl_add_u64 v[184:185], v[184:185], 0, v[26:27]
	v_fma_f32 v202, v70, v32, v6
	v_fma_f32 v203, v66, v32, v2
	v_fma_f32 v204, v71, v32, v7
	v_fma_f32 v205, v67, v32, v3
	v_fma_f32 v206, v72, v32, v8
; __device__ __forceinline__ float sigmoidf_(float x) { return frcp(1.0f + fexp(-x)); }
;     __device__ __forceinline__ void operator()(const Acc& acc, const Unit& u, int wr, int wc, int fr, int fq) const {
;     ...
;             for (int m = 0; m < 4; ++m) { const int row = row0 + ai * HALF + m * 16; const float rs = rsv[ai][m]; unsigned char* rowp = GT + (size_t)row * NGT + colt;
; #pragma unroll
;                 for (int bj = 0; bj < 2; ++bj) { f32x4 v0 = acc[ai][bj][m][0] * rs + bv[bj][0], v1 = acc[ai][bj][m][1] * rs + bv[bj][1];
;                     unsigned q0[4], q1[4];
; #pragma unroll
;                     for (int e = 0; e < 4; ++e) { q0[e] = (unsigned)fmaxf(sigmoidf_(v0[e]) * 255.0f + 0.5f, 1.0f); q1[e] = (unsigned)fmaxf(sigmoidf_(v1[e]) * 255.0f + 0.5f, 1.0f); }
;                     u32x2 w; w.x = q0[0] | (q0[1] << 8) | (q0[2] << 16) | (q0[3] << 24); w.y = q1[0] | (q1[1] << 8) | (q1[2] << 16) | (q1[3] << 24);
;                     *(u32x2*)(rowp + bj * HALF) = w; } }
	v_fma_f32 v207, v68, v32, v4
	v_fma_f32 v208, v73, v32, v9
	v_fma_f32 v209, v69, v32, v5
	v_exp_f32_e32 v202, v202
	v_exp_f32_e32 v203, v203
	v_exp_f32_e32 v204, v204
	v_exp_f32_e32 v205, v205
	v_exp_f32_e32 v206, v206
	v_exp_f32_e32 v207, v207
	v_exp_f32_e32 v208, v208
	v_exp_f32_e32 v209, v209
	s_nop 0
	v_fma_f32 v202, v202, s98, s98 clamp
	v_fma_f32 v203, v203, s98, s98 clamp
	v_fma_f32 v204, v204, s98, s98 clamp
	v_fma_f32 v205, v205, s98, s98 clamp
	v_fma_f32 v206, v206, s98, s98 clamp
	v_fma_f32 v207, v207, s98, s98 clamp
	v_fma_f32 v208, v208, s98, s98 clamp
	v_fma_f32 v209, v209, s98, s98 clamp
	v_rcp_f32_e32 v202, v202
	v_rcp_f32_e32 v203, v203
	v_rcp_f32_e32 v204, v204
	v_rcp_f32_e32 v205, v205
	v_rcp_f32_e32 v206, v206
	v_rcp_f32_e32 v207, v207
	v_rcp_f32_e32 v208, v208
	v_rcp_f32_e32 v209, v209
	s_nop 0
	v_cvt_pk_u8_f32 v220, v202, 0, 0
	v_cvt_pk_u8_f32 v220, v204, 1, v220
	v_cvt_pk_u8_f32 v220, v206, 2, v220
	v_cvt_pk_u8_f32 v220, v208, 3, v220
	v_cvt_pk_u8_f32 v221, v203, 0, 0
	v_cvt_pk_u8_f32 v221, v205, 1, v221
	v_cvt_pk_u8_f32 v221, v207, 2, v221
	v_cvt_pk_u8_f32 v221, v209, 3, v221
	v_add_u32_e32 v223, 0xa000, v222
	global_store_dwordx4 v223, v[218:221], s[88:89]
	v_mad_i64_i32 v[32:33], s[42:43], v181, s62, v[28:29]
	v_fma_f32 v202, v58, v31, v10
	v_fma_f32 v203, v59, v31, v11
	v_fma_f32 v204, v63, v31, v15
	v_fma_f32 v205, v60, v31, v12
	v_fma_f32 v206, v62, v31, v14
	v_fma_f32 v207, v64, v31, v16
	v_fma_f32 v208, v65, v31, v17
	v_fma_f32 v209, v61, v31, v13
	v_exp_f32_e32 v202, v202
	v_exp_f32_e32 v203, v203
	v_exp_f32_e32 v204, v204
	v_exp_f32_e32 v205, v205
	v_exp_f32_e32 v206, v206
	v_exp_f32_e32 v207, v207
	v_exp_f32_e32 v208, v208
	v_exp_f32_e32 v209, v209
	s_nop 0
	v_fma_f32 v202, v202, s98, s98 clamp
	v_fma_f32 v203, v203, s98, s98 clamp
	v_fma_f32 v204, v204, s98, s98 clamp
	v_fma_f32 v205, v205, s98, s98 clamp
	v_fma_f32 v206, v206, s98, s98 clamp
	v_fma_f32 v207, v207, s98, s98 clamp
	v_fma_f32 v208, v208, s98, s98 clamp
	v_fma_f32 v209, v209, s98, s98 clamp
	v_rcp_f32_e32 v202, v202
	v_rcp_f32_e32 v203, v203
	v_rcp_f32_e32 v204, v204
	v_rcp_f32_e32 v205, v205
	v_rcp_f32_e32 v206, v206
	v_rcp_f32_e32 v207, v207
	v_rcp_f32_e32 v208, v208
	v_rcp_f32_e32 v209, v209
	s_nop 0
	v_cvt_pk_u8_f32 v210, v206, 0, 0
	v_cvt_pk_u8_f32 v210, v204, 1, v210
	v_cvt_pk_u8_f32 v210, v207, 2, v210
	v_cvt_pk_u8_f32 v210, v208, 3, v210
	v_cvt_pk_u8_f32 v211, v202, 0, 0
	v_cvt_pk_u8_f32 v211, v203, 1, v211
	v_cvt_pk_u8_f32 v211, v205, 2, v211
	v_cvt_pk_u8_f32 v211, v209, 3, v211
	v_mad_i64_i32 v[28:29], s[42:43], v180, s62, v[28:29]
	v_lshl_add_u64 v[32:33], v[32:33], 0, v[26:27]
	v_lshl_add_u64 v[26:27], v[28:29], 0, v[26:27]
	v_fma_f32 v202, v42, v30, v10
	v_fma_f32 v203, v47, v30, v15
	v_fma_f32 v204, v43, v30, v11
	v_fma_f32 v205, v48, v30, v16
	v_fma_f32 v206, v44, v30, v12
	v_fma_f32 v207, v46, v30, v14
	v_fma_f32 v208, v49, v30, v17
	v_fma_f32 v209, v45, v30, v13
	v_exp_f32_e32 v202, v202
	v_exp_f32_e32 v203, v203
	v_exp_f32_e32 v204, v204
	v_exp_f32_e32 v205, v205
	v_exp_f32_e32 v206, v206
	v_exp_f32_e32 v207, v207
	v_exp_f32_e32 v208, v208
	v_exp_f32_e32 v209, v209
	s_nop 0
	v_fma_f32 v202, v202, s98, s98 clamp
	v_fma_f32 v203, v203, s98, s98 clamp
	v_fma_f32 v204, v204, s98, s98 clamp
	v_fma_f32 v205, v205, s98, s98 clamp
	v_fma_f32 v206, v206, s98, s98 clamp
	v_fma_f32 v207, v207, s98, s98 clamp
	v_fma_f32 v208, v208, s98, s98 clamp
	v_fma_f32 v209, v209, s98, s98 clamp
	v_rcp_f32_e32 v202, v202
	v_rcp_f32_e32 v203, v203
	v_rcp_f32_e32 v204, v204
	v_rcp_f32_e32 v205, v205
	v_rcp_f32_e32 v206, v206
	v_rcp_f32_e32 v207, v207
	v_rcp_f32_e32 v208, v208
	v_rcp_f32_e32 v209, v209
	s_nop 0
	v_cvt_pk_u8_f32 v214, v207, 0, 0
	v_cvt_pk_u8_f32 v214, v203, 1, v214
	v_cvt_pk_u8_f32 v214, v205, 2, v214
	v_cvt_pk_u8_f32 v214, v208, 3, v214
	v_cvt_pk_u8_f32 v215, v202, 0, 0
	v_cvt_pk_u8_f32 v215, v204, 1, v215
	v_cvt_pk_u8_f32 v215, v206, 2, v215
	v_cvt_pk_u8_f32 v215, v209, 3, v215
	v_fma_f32 v202, v50, v31, v2
	v_fma_f32 v203, v55, v31, v7
	v_fma_f32 v204, v51, v31, v3
	v_fma_f32 v205, v52, v31, v4
	v_fma_f32 v206, v54, v31, v6
	v_fma_f32 v207, v56, v31, v8
	v_fma_f32 v208, v57, v31, v9
	v_fma_f32 v209, v53, v31, v5
	v_exp_f32_e32 v202, v202
	v_exp_f32_e32 v203, v203
	v_exp_f32_e32 v204, v204
	v_exp_f32_e32 v205, v205
	v_exp_f32_e32 v206, v206
	v_exp_f32_e32 v207, v207
	v_exp_f32_e32 v208, v208
	v_exp_f32_e32 v209, v209
	s_nop 0
	v_fma_f32 v202, v202, s98, s98 clamp
	v_fma_f32 v203, v203, s98, s98 clamp
	v_fma_f32 v204, v204, s98, s98 clamp
	v_fma_f32 v205, v205, s98, s98 clamp
	v_fma_f32 v206, v206, s98, s98 clamp
	v_fma_f32 v207, v207, s98, s98 clamp
	v_fma_f32 v208, v208, s98, s98 clamp
	v_fma_f32 v209, v209, s98, s98 clamp
	v_rcp_f32_e32 v202, v202
	v_rcp_f32_e32 v203, v203
	v_rcp_f32_e32 v204, v204
	v_rcp_f32_e32 v205, v205
	v_rcp_f32_e32 v206, v206
	v_rcp_f32_e32 v207, v207
	v_rcp_f32_e32 v208, v208
	v_rcp_f32_e32 v209, v209
	s_nop 0
	v_cvt_pk_u8_f32 v212, v206, 0, 0
	v_cvt_pk_u8_f32 v212, v203, 1, v212
	v_cvt_pk_u8_f32 v212, v207, 2, v212
	v_cvt_pk_u8_f32 v212, v208, 3, v212
	v_cvt_pk_u8_f32 v213, v202, 0, 0
	v_cvt_pk_u8_f32 v213, v204, 1, v213
	v_cvt_pk_u8_f32 v213, v205, 2, v213
	v_cvt_pk_u8_f32 v213, v209, 3, v213
	v_fma_f32 v202, v34, v30, v2
	v_fma_f32 v203, v39, v30, v7
	v_fma_f32 v204, v35, v30, v3
	v_fma_f32 v205, v40, v30, v8
	v_fma_f32 v206, v36, v30, v4
	v_fma_f32 v207, v38, v30, v6
	v_fma_f32 v208, v41, v30, v9
	v_fma_f32 v209, v37, v30, v5
	v_exp_f32_e32 v202, v202
	v_exp_f32_e32 v203, v203
	v_exp_f32_e32 v204, v204
	v_exp_f32_e32 v205, v205
	v_exp_f32_e32 v206, v206
	v_exp_f32_e32 v207, v207
	v_exp_f32_e32 v208, v208
	v_exp_f32_e32 v209, v209
	s_nop 0
	v_fma_f32 v202, v202, s98, s98 clamp
	v_fma_f32 v203, v203, s98, s98 clamp
	v_fma_f32 v204, v204, s98, s98 clamp
	v_fma_f32 v205, v205, s98, s98 clamp
	v_fma_f32 v206, v206, s98, s98 clamp
	v_fma_f32 v207, v207, s98, s98 clamp
	v_fma_f32 v208, v208, s98, s98 clamp
	v_fma_f32 v209, v209, s98, s98 clamp
	v_rcp_f32_e32 v202, v202
	v_rcp_f32_e32 v203, v203
	v_rcp_f32_e32 v204, v204
	v_rcp_f32_e32 v205, v205
	v_rcp_f32_e32 v206, v206
	v_rcp_f32_e32 v207, v207
	v_rcp_f32_e32 v208, v208
	v_rcp_f32_e32 v209, v209
	s_nop 0
	v_cvt_pk_u8_f32 v216, v207, 0, 0
	v_cvt_pk_u8_f32 v216, v203, 1, v216
	v_cvt_pk_u8_f32 v216, v205, 2, v216
	v_cvt_pk_u8_f32 v216, v208, 3, v216
	v_cvt_pk_u8_f32 v217, v202, 0, 0
	v_cvt_pk_u8_f32 v217, v204, 1, v217
	v_cvt_pk_u8_f32 v217, v206, 2, v217
	v_cvt_pk_u8_f32 v217, v209, 3, v217
	v_add_u32_e32 v223, 0xc000, v222
	global_store_dwordx4 v223, v[210:213], s[88:89]
	v_add_u32_e32 v223, 0xe000, v222
	global_store_dwordx4 v223, v[214:217], s[88:89]
	s_cbranch_execz .LBB0_574

; __device__ __forceinline__ float frcp(float x) { return __builtin_amdgcn_rcpf(x); }
;     static __device__ __forceinline__ float ub(unsigned w, int i) { return (float)((w >> (8 * i)) & 0xffu); }
;     __device__ __forceinline__ void chain(Acc& acc, const Unit& u, int wr, int wc, int fr, int fq) const {
;         const int row0 = u.pm * BM + wr * 64 + fr; const int col0 = u.pn * BM + wc * 32 + 8 * fq;
;         const int sub = u.sub, subn = (u.sub < 2) ? u.sub + 1 : 2;
; #pragma unroll
;         for (int ai = 0; ai < 2; ++ai) {
;             u32x2 g[4][2], h[4][2];
; #pragma unroll
;             for (int m = 0; m < 4; ++m)
; #pragma unroll
;                 for (int bj = 0; bj < 2; ++bj) { const unsigned char* p = GT + (size_t)(row0 + ai * HALF + m * 16) * NGT + col0 + bj * HALF;
;                     g[m][bj] = *(const u32x2*)(p + sub * DM); h[m][bj] = *(const u32x2*)(p + subn * DM); }
; #pragma unroll
;             for (int m = 0; m < 4; ++m)
; #pragma unroll
;                 for (int bj = 0; bj < 2; ++bj) { const u32x2 gg = g[m][bj], hh = h[m][bj];
;                     float sc[8];
;                     if (sub < 2) {
; #pragma unroll
;                         for (int e = 0; e < 8; ++e) sc[e] = ub(e < 4 ? gg.x : gg.y, e & 3) * frcp(ub(e < 4 ? hh.x : hh.y, e & 3));
;                     } else {
; #pragma unroll
;                         for (int e = 0; e < 8; ++e) sc[e] = ub(e < 4 ? gg.x : gg.y, e & 3) * (1.0f / 255.0f);
;                     }
;                     f32x4 a0 = acc[ai][bj][m][0], a1 = acc[ai][bj][m][1];
;                     a0 *= (f32x4){sc[0], sc[1], sc[2], sc[3]}; a1 *= (f32x4){sc[4], sc[5], sc[6], sc[7]};
;                     if (sub < 2) { acc[ai][bj][m][0] = a0; acc[ai][bj][m][1] = a1; }
.LBB0_875:
	v_lshl_add_u32 v234, s40, 8, v206
	v_lshl_or_b32 v235, s38, 8, v208
	s_mul_i32 s25, s40, 24
	s_lshl_b32 s41, s39, 3
	s_add_i32 s25, s25, s41
	s_add_i32 s25, s25, s38
	s_lshl_b32 s25, s25, 16
	v_lshlrev_b32_e32 v236, 4, v0
	s_add_u32 s40, s10, s25
	s_addc_u32 s41, s11, 0
	v_add_u32_e32 v237, 0x2000, v236
	v_add_u32_e32 v238, 0x4000, v236
	v_add_u32_e32 v239, 0x6000, v236
	v_add_u32_e32 v240, 0x8000, v236
	v_add_u32_e32 v241, 0xa000, v236
	v_add_u32_e32 v242, 0xc000, v236
	v_add_u32_e32 v243, 0xe000, v236
	s_cmp_eq_u32 s39, 2
	s_cbranch_scc1 .Lp3c_last
	s_add_u32 s38, s40, 0x80000
	s_addc_u32 s39, s41, 0
	global_load_dwordx4 v[190:193], v236, s[40:41]
	global_load_dwordx4 v[46:49], v236, s[38:39]
	global_load_dwordx4 v[194:197], v237, s[40:41]
	global_load_dwordx4 v[50:53], v237, s[38:39]
	global_load_dwordx4 v[198:201], v238, s[40:41]
	global_load_dwordx4 v[78:81], v238, s[38:39]
	global_load_dwordx4 v[202:205], v239, s[40:41]
	global_load_dwordx4 v[82:85], v239, s[38:39]
	global_load_dwordx4 v[210:213], v240, s[40:41]
	global_load_dwordx4 v[110:113], v240, s[38:39]
	global_load_dwordx4 v[214:217], v241, s[40:41]
	global_load_dwordx4 v[114:117], v241, s[38:39]
	global_load_dwordx4 v[218:221], v242, s[40:41]
	global_load_dwordx4 v[142:145], v242, s[38:39]
	global_load_dwordx4 v[222:225], v243, s[40:41]
	global_load_dwordx4 v[146:149], v243, s[38:39]
	s_waitcnt vmcnt(14)
	v_cvt_f32_ubyte0_e32 v226, v46
	v_cvt_f32_ubyte1_e32 v227, v46
	v_cvt_f32_ubyte2_e32 v228, v46
	v_cvt_f32_ubyte3_e32 v229, v46
	v_cvt_f32_ubyte0_e32 v230, v47
	v_cvt_f32_ubyte1_e32 v231, v47
	v_cvt_f32_ubyte2_e32 v232, v47
	v_cvt_f32_ubyte3_e32 v233, v47
	v_cvt_f32_ubyte0_e32 v2, v190
	v_cvt_f32_ubyte1_e32 v3, v190
	v_cvt_f32_ubyte2_e32 v4, v190
	v_cvt_f32_ubyte3_e32 v5, v190
	v_cvt_f32_ubyte0_e32 v6, v191
	v_cvt_f32_ubyte1_e32 v7, v191
	v_cvt_f32_ubyte2_e32 v8, v191
	v_cvt_f32_ubyte3_e32 v9, v191
	v_rcp_iflag_f32_e32 v226, v226
	v_rcp_iflag_f32_e32 v227, v227
	v_rcp_iflag_f32_e32 v228, v228
	v_rcp_iflag_f32_e32 v229, v229
	v_rcp_iflag_f32_e32 v230, v230
	v_rcp_iflag_f32_e32 v231, v231
	v_rcp_iflag_f32_e32 v232, v232
	v_rcp_iflag_f32_e32 v233, v233
	s_nop 0
	v_pk_mul_f32 v[2:3], v[226:227], v[2:3]
	v_pk_mul_f32 v[4:5], v[228:229], v[4:5]
	v_pk_mul_f32 v[6:7], v[230:231], v[6:7]
	v_pk_mul_f32 v[8:9], v[232:233], v[8:9]
	v_pk_mul_f32 v[66:67], v[66:67], v[2:3]
	v_pk_mul_f32 v[68:69], v[68:69], v[4:5]
	v_pk_mul_f32 v[62:63], v[62:63], v[6:7]
	v_pk_mul_f32 v[64:65], v[64:65], v[8:9]
	v_cvt_f32_ubyte0_e32 v226, v48
	v_cvt_f32_ubyte1_e32 v227, v48
	v_cvt_f32_ubyte2_e32 v228, v48
	v_cvt_f32_ubyte3_e32 v229, v48
	v_cvt_f32_ubyte0_e32 v230, v49
	v_cvt_f32_ubyte1_e32 v231, v49
	v_cvt_f32_ubyte2_e32 v232, v49
	v_cvt_f32_ubyte3_e32 v233, v49
	v_cvt_f32_ubyte0_e32 v2, v192
	v_cvt_f32_ubyte1_e32 v3, v192
	v_cvt_f32_ubyte2_e32 v4, v192
	v_cvt_f32_ubyte3_e32 v5, v192
	v_cvt_f32_ubyte0_e32 v6, v193
	v_cvt_f32_ubyte1_e32 v7, v193
	v_cvt_f32_ubyte2_e32 v8, v193
	v_cvt_f32_ubyte3_e32 v9, v193
	v_rcp_iflag_f32_e32 v226, v226
	v_rcp_iflag_f32_e32 v227, v227
	v_rcp_iflag_f32_e32 v228, v228
	v_rcp_iflag_f32_e32 v229, v229
	v_rcp_iflag_f32_e32 v230, v230
	v_rcp_iflag_f32_e32 v231, v231
	v_rcp_iflag_f32_e32 v232, v232
	v_rcp_iflag_f32_e32 v233, v233
	s_nop 0
	v_pk_mul_f32 v[2:3], v[226:227], v[2:3]
	v_pk_mul_f32 v[4:5], v[228:229], v[4:5]
	v_pk_mul_f32 v[6:7], v[230:231], v[6:7]
	v_pk_mul_f32 v[8:9], v[232:233], v[8:9]
	v_pk_mul_f32 v[170:171], v[170:171], v[2:3]
	v_pk_mul_f32 v[172:173], v[172:173], v[4:5]
	v_pk_mul_f32 v[166:167], v[166:167], v[6:7]
	v_pk_mul_f32 v[168:169], v[168:169], v[8:9]
	s_waitcnt vmcnt(12)
	v_cvt_f32_ubyte0_e32 v226, v50
	v_cvt_f32_ubyte1_e32 v227, v50
	v_cvt_f32_ubyte2_e32 v228, v50
	v_cvt_f32_ubyte3_e32 v229, v50
	v_cvt_f32_ubyte0_e32 v230, v51
	v_cvt_f32_ubyte1_e32 v231, v51
	v_cvt_f32_ubyte2_e32 v232, v51
	v_cvt_f32_ubyte3_e32 v233, v51
	v_cvt_f32_ubyte0_e32 v2, v194
	v_cvt_f32_ubyte1_e32 v3, v194
	v_cvt_f32_ubyte2_e32 v4, v194
	v_cvt_f32_ubyte3_e32 v5, v194
	v_cvt_f32_ubyte0_e32 v6, v195
	v_cvt_f32_ubyte1_e32 v7, v195
	v_cvt_f32_ubyte2_e32 v8, v195
	v_cvt_f32_ubyte3_e32 v9, v195
	v_rcp_iflag_f32_e32 v226, v226
	v_rcp_iflag_f32_e32 v227, v227
	v_rcp_iflag_f32_e32 v228, v228
	v_rcp_iflag_f32_e32 v229, v229
	v_rcp_iflag_f32_e32 v230, v230
	v_rcp_iflag_f32_e32 v231, v231
	v_rcp_iflag_f32_e32 v232, v232
	v_rcp_iflag_f32_e32 v233, v233
	s_nop 0
	v_pk_mul_f32 v[2:3], v[226:227], v[2:3]
	v_pk_mul_f32 v[4:5], v[228:229], v[4:5]
	v_pk_mul_f32 v[6:7], v[230:231], v[6:7]
	v_pk_mul_f32 v[8:9], v[232:233], v[8:9]
	v_pk_mul_f32 v[98:99], v[98:99], v[2:3]
	v_pk_mul_f32 v[100:101], v[100:101], v[4:5]
	v_pk_mul_f32 v[94:95], v[94:95], v[6:7]
	v_pk_mul_f32 v[96:97], v[96:97], v[8:9]
	v_cvt_f32_ubyte0_e32 v226, v52
	v_cvt_f32_ubyte1_e32 v227, v52
	v_cvt_f32_ubyte2_e32 v228, v52
	v_cvt_f32_ubyte3_e32 v229, v52
	v_cvt_f32_ubyte0_e32 v230, v53
	v_cvt_f32_ubyte1_e32 v231, v53
	v_cvt_f32_ubyte2_e32 v232, v53
	v_cvt_f32_ubyte3_e32 v233, v53
	v_cvt_f32_ubyte0_e32 v2, v196
	v_cvt_f32_ubyte1_e32 v3, v196
	v_cvt_f32_ubyte2_e32 v4, v196
	v_cvt_f32_ubyte3_e32 v5, v196
	v_cvt_f32_ubyte0_e32 v6, v197
	v_cvt_f32_ubyte1_e32 v7, v197
	v_cvt_f32_ubyte2_e32 v8, v197
	v_cvt_f32_ubyte3_e32 v9, v197
	v_rcp_iflag_f32_e32 v226, v226
	v_rcp_iflag_f32_e32 v227, v227
	v_rcp_iflag_f32_e32 v228, v228
	v_rcp_iflag_f32_e32 v229, v229
	v_rcp_iflag_f32_e32 v230, v230
	v_rcp_iflag_f32_e32 v231, v231
	v_rcp_iflag_f32_e32 v232, v232
	v_rcp_iflag_f32_e32 v233, v233
	s_nop 0
	v_pk_mul_f32 v[2:3], v[226:227], v[2:3]
	v_pk_mul_f32 v[4:5], v[228:229], v[4:5]
	v_pk_mul_f32 v[6:7], v[230:231], v[6:7]
	v_pk_mul_f32 v[8:9], v[232:233], v[8:9]
	v_pk_mul_f32 v[162:163], v[162:163], v[2:3]
	v_pk_mul_f32 v[164:165], v[164:165], v[4:5]
	v_pk_mul_f32 v[158:159], v[158:159], v[6:7]
	v_pk_mul_f32 v[160:161], v[160:161], v[8:9]
	s_waitcnt vmcnt(10)
; __device__ __forceinline__ float frcp(float x) { return __builtin_amdgcn_rcpf(x); }
;     static __device__ __forceinline__ float ub(unsigned w, int i) { return (float)((w >> (8 * i)) & 0xffu); }
;     __device__ __forceinline__ void chain(Acc& acc, const Unit& u, int wr, int wc, int fr, int fq) const {
;     ...
;             for (int m = 0; m < 4; ++m)
; #pragma unroll
;                 for (int bj = 0; bj < 2; ++bj) { const u32x2 gg = g[m][bj], hh = h[m][bj];
;                     float sc[8];
;                     if (sub < 2) {
; #pragma unroll
;                         for (int e = 0; e < 8; ++e) sc[e] = ub(e < 4 ? gg.x : gg.y, e & 3) * frcp(ub(e < 4 ? hh.x : hh.y, e & 3));
;                     } else {
; #pragma unroll
;                         for (int e = 0; e < 8; ++e) sc[e] = ub(e < 4 ? gg.x : gg.y, e & 3) * (1.0f / 255.0f);
;                     }
;                     f32x4 a0 = acc[ai][bj][m][0], a1 = acc[ai][bj][m][1];
;                     a0 *= (f32x4){sc[0], sc[1], sc[2], sc[3]}; a1 *= (f32x4){sc[4], sc[5], sc[6], sc[7]};
;                     if (sub < 2) { acc[ai][bj][m][0] = a0; acc[ai][bj][m][1] = a1; }
	v_cvt_f32_ubyte0_e32 v226, v78
	v_cvt_f32_ubyte1_e32 v227, v78
	v_cvt_f32_ubyte2_e32 v228, v78
	v_cvt_f32_ubyte3_e32 v229, v78
	v_cvt_f32_ubyte0_e32 v230, v79
	v_cvt_f32_ubyte1_e32 v231, v79
	v_cvt_f32_ubyte2_e32 v232, v79
	v_cvt_f32_ubyte3_e32 v233, v79
	v_cvt_f32_ubyte0_e32 v2, v198
	v_cvt_f32_ubyte1_e32 v3, v198
	v_cvt_f32_ubyte2_e32 v4, v198
	v_cvt_f32_ubyte3_e32 v5, v198
	v_cvt_f32_ubyte0_e32 v6, v199
	v_cvt_f32_ubyte1_e32 v7, v199
	v_cvt_f32_ubyte2_e32 v8, v199
	v_cvt_f32_ubyte3_e32 v9, v199
	v_rcp_iflag_f32_e32 v226, v226
	v_rcp_iflag_f32_e32 v227, v227
	v_rcp_iflag_f32_e32 v228, v228
	v_rcp_iflag_f32_e32 v229, v229
	v_rcp_iflag_f32_e32 v230, v230
	v_rcp_iflag_f32_e32 v231, v231
	v_rcp_iflag_f32_e32 v232, v232
	v_rcp_iflag_f32_e32 v233, v233
	s_nop 0
	v_pk_mul_f32 v[2:3], v[226:227], v[2:3]
	v_pk_mul_f32 v[4:5], v[228:229], v[4:5]
	v_pk_mul_f32 v[6:7], v[230:231], v[6:7]
	v_pk_mul_f32 v[8:9], v[232:233], v[8:9]
	v_pk_mul_f32 v[130:131], v[130:131], v[2:3]
	v_pk_mul_f32 v[132:133], v[132:133], v[4:5]
	v_pk_mul_f32 v[126:127], v[126:127], v[6:7]
	v_pk_mul_f32 v[128:129], v[128:129], v[8:9]
	v_cvt_f32_ubyte0_e32 v226, v80
	v_cvt_f32_ubyte1_e32 v227, v80
	v_cvt_f32_ubyte2_e32 v228, v80
	v_cvt_f32_ubyte3_e32 v229, v80
	v_cvt_f32_ubyte0_e32 v230, v81
	v_cvt_f32_ubyte1_e32 v231, v81
	v_cvt_f32_ubyte2_e32 v232, v81
	v_cvt_f32_ubyte3_e32 v233, v81
	v_cvt_f32_ubyte0_e32 v2, v200
	v_cvt_f32_ubyte1_e32 v3, v200
	v_cvt_f32_ubyte2_e32 v4, v200
	v_cvt_f32_ubyte3_e32 v5, v200
	v_cvt_f32_ubyte0_e32 v6, v201
	v_cvt_f32_ubyte1_e32 v7, v201
	v_cvt_f32_ubyte2_e32 v8, v201
	v_cvt_f32_ubyte3_e32 v9, v201
	v_rcp_iflag_f32_e32 v226, v226
	v_rcp_iflag_f32_e32 v227, v227
	v_rcp_iflag_f32_e32 v228, v228
	v_rcp_iflag_f32_e32 v229, v229
	v_rcp_iflag_f32_e32 v230, v230
	v_rcp_iflag_f32_e32 v231, v231
	v_rcp_iflag_f32_e32 v232, v232
	v_rcp_iflag_f32_e32 v233, v233
	s_nop 0
	v_pk_mul_f32 v[2:3], v[226:227], v[2:3]
	v_pk_mul_f32 v[4:5], v[228:229], v[4:5]
	v_pk_mul_f32 v[6:7], v[230:231], v[6:7]
	v_pk_mul_f32 v[8:9], v[232:233], v[8:9]
	v_pk_mul_f32 v[154:155], v[154:155], v[2:3]
	v_pk_mul_f32 v[156:157], v[156:157], v[4:5]
	v_pk_mul_f32 v[150:151], v[150:151], v[6:7]
	v_pk_mul_f32 v[152:153], v[152:153], v[8:9]
	s_waitcnt vmcnt(8)
	v_cvt_f32_ubyte0_e32 v226, v82
	v_cvt_f32_ubyte1_e32 v227, v82
	v_cvt_f32_ubyte2_e32 v228, v82
	v_cvt_f32_ubyte3_e32 v229, v82
	v_cvt_f32_ubyte0_e32 v230, v83
	v_cvt_f32_ubyte1_e32 v231, v83
	v_cvt_f32_ubyte2_e32 v232, v83
	v_cvt_f32_ubyte3_e32 v233, v83
	v_cvt_f32_ubyte0_e32 v2, v202
	v_cvt_f32_ubyte1_e32 v3, v202
	v_cvt_f32_ubyte2_e32 v4, v202
	v_cvt_f32_ubyte3_e32 v5, v202
	v_cvt_f32_ubyte0_e32 v6, v203
	v_cvt_f32_ubyte1_e32 v7, v203
	v_cvt_f32_ubyte2_e32 v8, v203
	v_cvt_f32_ubyte3_e32 v9, v203
	v_rcp_iflag_f32_e32 v226, v226
	v_rcp_iflag_f32_e32 v227, v227
	v_rcp_iflag_f32_e32 v228, v228
	v_rcp_iflag_f32_e32 v229, v229
	v_rcp_iflag_f32_e32 v230, v230
	v_rcp_iflag_f32_e32 v231, v231
	v_rcp_iflag_f32_e32 v232, v232
	v_rcp_iflag_f32_e32 v233, v233
	s_nop 0
	v_pk_mul_f32 v[2:3], v[226:227], v[2:3]
	v_pk_mul_f32 v[4:5], v[228:229], v[4:5]
	v_pk_mul_f32 v[6:7], v[230:231], v[6:7]
	v_pk_mul_f32 v[8:9], v[232:233], v[8:9]
	v_pk_mul_f32 v[138:139], v[138:139], v[2:3]
	v_pk_mul_f32 v[140:141], v[140:141], v[4:5]
	v_pk_mul_f32 v[134:135], v[134:135], v[6:7]
	v_pk_mul_f32 v[136:137], v[136:137], v[8:9]
	v_cvt_f32_ubyte0_e32 v226, v84
	v_cvt_f32_ubyte1_e32 v227, v84
	v_cvt_f32_ubyte2_e32 v228, v84
	v_cvt_f32_ubyte3_e32 v229, v84
	v_cvt_f32_ubyte0_e32 v230, v85
	v_cvt_f32_ubyte1_e32 v231, v85
	v_cvt_f32_ubyte2_e32 v232, v85
	v_cvt_f32_ubyte3_e32 v233, v85
	v_cvt_f32_ubyte0_e32 v2, v204
	v_cvt_f32_ubyte1_e32 v3, v204
	v_cvt_f32_ubyte2_e32 v4, v204
	v_cvt_f32_ubyte3_e32 v5, v204
	v_cvt_f32_ubyte0_e32 v6, v205
	v_cvt_f32_ubyte1_e32 v7, v205
	v_cvt_f32_ubyte2_e32 v8, v205
	v_cvt_f32_ubyte3_e32 v9, v205
	v_rcp_iflag_f32_e32 v226, v226
	v_rcp_iflag_f32_e32 v227, v227
	v_rcp_iflag_f32_e32 v228, v228
	v_rcp_iflag_f32_e32 v229, v229
	v_rcp_iflag_f32_e32 v230, v230
	v_rcp_iflag_f32_e32 v231, v231
	v_rcp_iflag_f32_e32 v232, v232
	v_rcp_iflag_f32_e32 v233, v233
	s_nop 0
	v_pk_mul_f32 v[2:3], v[226:227], v[2:3]
	v_pk_mul_f32 v[4:5], v[228:229], v[4:5]
	v_pk_mul_f32 v[6:7], v[230:231], v[6:7]
	v_pk_mul_f32 v[8:9], v[232:233], v[8:9]
	v_pk_mul_f32 v[122:123], v[122:123], v[2:3]
	v_pk_mul_f32 v[124:125], v[124:125], v[4:5]
	v_pk_mul_f32 v[118:119], v[118:119], v[6:7]
	v_pk_mul_f32 v[120:121], v[120:121], v[8:9]
	s_waitcnt vmcnt(6)
	v_cvt_f32_ubyte0_e32 v226, v110
	v_cvt_f32_ubyte1_e32 v227, v110
	v_cvt_f32_ubyte2_e32 v228, v110
	v_cvt_f32_ubyte3_e32 v229, v110
	v_cvt_f32_ubyte0_e32 v230, v111
	v_cvt_f32_ubyte1_e32 v231, v111
	v_cvt_f32_ubyte2_e32 v232, v111
	v_cvt_f32_ubyte3_e32 v233, v111
	v_cvt_f32_ubyte0_e32 v2, v210
	v_cvt_f32_ubyte1_e32 v3, v210
	v_cvt_f32_ubyte2_e32 v4, v210
	v_cvt_f32_ubyte3_e32 v5, v210
	v_cvt_f32_ubyte0_e32 v6, v211
	v_cvt_f32_ubyte1_e32 v7, v211
	v_cvt_f32_ubyte2_e32 v8, v211
	v_cvt_f32_ubyte3_e32 v9, v211
	v_rcp_iflag_f32_e32 v226, v226
	v_rcp_iflag_f32_e32 v227, v227
	v_rcp_iflag_f32_e32 v228, v228
	v_rcp_iflag_f32_e32 v229, v229
	v_rcp_iflag_f32_e32 v230, v230
	v_rcp_iflag_f32_e32 v231, v231
	v_rcp_iflag_f32_e32 v232, v232
	v_rcp_iflag_f32_e32 v233, v233
	s_nop 0
	v_pk_mul_f32 v[2:3], v[226:227], v[2:3]
	v_pk_mul_f32 v[4:5], v[228:229], v[4:5]
	v_pk_mul_f32 v[6:7], v[230:231], v[6:7]
	v_pk_mul_f32 v[8:9], v[232:233], v[8:9]
	v_pk_mul_f32 v[106:107], v[106:107], v[2:3]
	v_pk_mul_f32 v[108:109], v[108:109], v[4:5]
	v_pk_mul_f32 v[102:103], v[102:103], v[6:7]
	v_pk_mul_f32 v[104:105], v[104:105], v[8:9]
	v_cvt_f32_ubyte0_e32 v226, v112
	v_cvt_f32_ubyte1_e32 v227, v112
	v_cvt_f32_ubyte2_e32 v228, v112
	v_cvt_f32_ubyte3_e32 v229, v112
	v_cvt_f32_ubyte0_e32 v230, v113
	v_cvt_f32_ubyte1_e32 v231, v113
	v_cvt_f32_ubyte2_e32 v232, v113
	v_cvt_f32_ubyte3_e32 v233, v113
	v_cvt_f32_ubyte0_e32 v2, v212
	v_cvt_f32_ubyte1_e32 v3, v212
	v_cvt_f32_ubyte2_e32 v4, v212
	v_cvt_f32_ubyte3_e32 v5, v212
	v_cvt_f32_ubyte0_e32 v6, v213
	v_cvt_f32_ubyte1_e32 v7, v213
	v_cvt_f32_ubyte2_e32 v8, v213
	v_cvt_f32_ubyte3_e32 v9, v213
	v_rcp_iflag_f32_e32 v226, v226
	v_rcp_iflag_f32_e32 v227, v227
	v_rcp_iflag_f32_e32 v228, v228
	v_rcp_iflag_f32_e32 v229, v229
	v_rcp_iflag_f32_e32 v230, v230
	v_rcp_iflag_f32_e32 v231, v231
	v_rcp_iflag_f32_e32 v232, v232
	v_rcp_iflag_f32_e32 v233, v233
	s_nop 0
	v_pk_mul_f32 v[2:3], v[226:227], v[2:3]
	v_pk_mul_f32 v[4:5], v[228:229], v[4:5]
	v_pk_mul_f32 v[6:7], v[230:231], v[6:7]
	v_pk_mul_f32 v[8:9], v[232:233], v[8:9]
	v_pk_mul_f32 v[90:91], v[90:91], v[2:3]
	v_pk_mul_f32 v[92:93], v[92:93], v[4:5]
	v_pk_mul_f32 v[86:87], v[86:87], v[6:7]
	v_pk_mul_f32 v[88:89], v[88:89], v[8:9]
	s_waitcnt vmcnt(4)
; __device__ __forceinline__ float frcp(float x) { return __builtin_amdgcn_rcpf(x); }
;     static __device__ __forceinline__ float ub(unsigned w, int i) { return (float)((w >> (8 * i)) & 0xffu); }
;     __device__ __forceinline__ void chain(Acc& acc, const Unit& u, int wr, int wc, int fr, int fq) const {
;     ...
;             for (int m = 0; m < 4; ++m)
; #pragma unroll
;                 for (int bj = 0; bj < 2; ++bj) { const u32x2 gg = g[m][bj], hh = h[m][bj];
;                     float sc[8];
;                     if (sub < 2) {
; #pragma unroll
;                         for (int e = 0; e < 8; ++e) sc[e] = ub(e < 4 ? gg.x : gg.y, e & 3) * frcp(ub(e < 4 ? hh.x : hh.y, e & 3));
;                     } else {
; #pragma unroll
;                         for (int e = 0; e < 8; ++e) sc[e] = ub(e < 4 ? gg.x : gg.y, e & 3) * (1.0f / 255.0f);
;                     }
;                     f32x4 a0 = acc[ai][bj][m][0], a1 = acc[ai][bj][m][1];
;                     a0 *= (f32x4){sc[0], sc[1], sc[2], sc[3]}; a1 *= (f32x4){sc[4], sc[5], sc[6], sc[7]};
;                     if (sub < 2) { acc[ai][bj][m][0] = a0; acc[ai][bj][m][1] = a1; }
	v_cvt_f32_ubyte0_e32 v226, v114
	v_cvt_f32_ubyte1_e32 v227, v114
	v_cvt_f32_ubyte2_e32 v228, v114
	v_cvt_f32_ubyte3_e32 v229, v114
	v_cvt_f32_ubyte0_e32 v230, v115
	v_cvt_f32_ubyte1_e32 v231, v115
	v_cvt_f32_ubyte2_e32 v232, v115
	v_cvt_f32_ubyte3_e32 v233, v115
	v_cvt_f32_ubyte0_e32 v2, v214
	v_cvt_f32_ubyte1_e32 v3, v214
	v_cvt_f32_ubyte2_e32 v4, v214
	v_cvt_f32_ubyte3_e32 v5, v214
	v_cvt_f32_ubyte0_e32 v6, v215
	v_cvt_f32_ubyte1_e32 v7, v215
	v_cvt_f32_ubyte2_e32 v8, v215
	v_cvt_f32_ubyte3_e32 v9, v215
	v_rcp_iflag_f32_e32 v226, v226
	v_rcp_iflag_f32_e32 v227, v227
	v_rcp_iflag_f32_e32 v228, v228
	v_rcp_iflag_f32_e32 v229, v229
	v_rcp_iflag_f32_e32 v230, v230
	v_rcp_iflag_f32_e32 v231, v231
	v_rcp_iflag_f32_e32 v232, v232
	v_rcp_iflag_f32_e32 v233, v233
	s_nop 0
	v_pk_mul_f32 v[2:3], v[226:227], v[2:3]
	v_pk_mul_f32 v[4:5], v[228:229], v[4:5]
	v_pk_mul_f32 v[6:7], v[230:231], v[6:7]
	v_pk_mul_f32 v[8:9], v[232:233], v[8:9]
	v_pk_mul_f32 v[74:75], v[74:75], v[2:3]
	v_pk_mul_f32 v[76:77], v[76:77], v[4:5]
	v_pk_mul_f32 v[70:71], v[70:71], v[6:7]
	v_pk_mul_f32 v[72:73], v[72:73], v[8:9]
	v_cvt_f32_ubyte0_e32 v226, v116
	v_cvt_f32_ubyte1_e32 v227, v116
	v_cvt_f32_ubyte2_e32 v228, v116
	v_cvt_f32_ubyte3_e32 v229, v116
	v_cvt_f32_ubyte0_e32 v230, v117
	v_cvt_f32_ubyte1_e32 v231, v117
	v_cvt_f32_ubyte2_e32 v232, v117
	v_cvt_f32_ubyte3_e32 v233, v117
	v_cvt_f32_ubyte0_e32 v2, v216
	v_cvt_f32_ubyte1_e32 v3, v216
	v_cvt_f32_ubyte2_e32 v4, v216
	v_cvt_f32_ubyte3_e32 v5, v216
	v_cvt_f32_ubyte0_e32 v6, v217
	v_cvt_f32_ubyte1_e32 v7, v217
	v_cvt_f32_ubyte2_e32 v8, v217
	v_cvt_f32_ubyte3_e32 v9, v217
	v_rcp_iflag_f32_e32 v226, v226
	v_rcp_iflag_f32_e32 v227, v227
	v_rcp_iflag_f32_e32 v228, v228
	v_rcp_iflag_f32_e32 v229, v229
	v_rcp_iflag_f32_e32 v230, v230
	v_rcp_iflag_f32_e32 v231, v231
	v_rcp_iflag_f32_e32 v232, v232
	v_rcp_iflag_f32_e32 v233, v233
	s_nop 0
	v_pk_mul_f32 v[2:3], v[226:227], v[2:3]
	v_pk_mul_f32 v[4:5], v[228:229], v[4:5]
	v_pk_mul_f32 v[6:7], v[230:231], v[6:7]
	v_pk_mul_f32 v[8:9], v[232:233], v[8:9]
	v_pk_mul_f32 v[58:59], v[58:59], v[2:3]
	v_pk_mul_f32 v[60:61], v[60:61], v[4:5]
	v_pk_mul_f32 v[54:55], v[54:55], v[6:7]
	v_pk_mul_f32 v[56:57], v[56:57], v[8:9]
	s_waitcnt vmcnt(2)
	v_cvt_f32_ubyte0_e32 v226, v142
	v_cvt_f32_ubyte1_e32 v227, v142
	v_cvt_f32_ubyte2_e32 v228, v142
	v_cvt_f32_ubyte3_e32 v229, v142
	v_cvt_f32_ubyte0_e32 v230, v143
	v_cvt_f32_ubyte1_e32 v231, v143
	v_cvt_f32_ubyte2_e32 v232, v143
	v_cvt_f32_ubyte3_e32 v233, v143
	v_cvt_f32_ubyte0_e32 v2, v218
	v_cvt_f32_ubyte1_e32 v3, v218
	v_cvt_f32_ubyte2_e32 v4, v218
	v_cvt_f32_ubyte3_e32 v5, v218
	v_cvt_f32_ubyte0_e32 v6, v219
	v_cvt_f32_ubyte1_e32 v7, v219
	v_cvt_f32_ubyte2_e32 v8, v219
	v_cvt_f32_ubyte3_e32 v9, v219
	v_rcp_iflag_f32_e32 v226, v226
	v_rcp_iflag_f32_e32 v227, v227
	v_rcp_iflag_f32_e32 v228, v228
	v_rcp_iflag_f32_e32 v229, v229
	v_rcp_iflag_f32_e32 v230, v230
	v_rcp_iflag_f32_e32 v231, v231
	v_rcp_iflag_f32_e32 v232, v232
	v_rcp_iflag_f32_e32 v233, v233
	s_nop 0
	v_pk_mul_f32 v[2:3], v[226:227], v[2:3]
	v_pk_mul_f32 v[4:5], v[228:229], v[4:5]
	v_pk_mul_f32 v[6:7], v[230:231], v[6:7]
	v_pk_mul_f32 v[8:9], v[232:233], v[8:9]
	v_pk_mul_f32 v[42:43], v[42:43], v[2:3]
	v_pk_mul_f32 v[44:45], v[44:45], v[4:5]
	v_pk_mul_f32 v[38:39], v[38:39], v[6:7]
	v_pk_mul_f32 v[40:41], v[40:41], v[8:9]
	v_cvt_f32_ubyte0_e32 v226, v144
	v_cvt_f32_ubyte1_e32 v227, v144
	v_cvt_f32_ubyte2_e32 v228, v144
	v_cvt_f32_ubyte3_e32 v229, v144
	v_cvt_f32_ubyte0_e32 v230, v145
	v_cvt_f32_ubyte1_e32 v231, v145
	v_cvt_f32_ubyte2_e32 v232, v145
	v_cvt_f32_ubyte3_e32 v233, v145
	v_cvt_f32_ubyte0_e32 v2, v220
	v_cvt_f32_ubyte1_e32 v3, v220
	v_cvt_f32_ubyte2_e32 v4, v220
	v_cvt_f32_ubyte3_e32 v5, v220
	v_cvt_f32_ubyte0_e32 v6, v221
	v_cvt_f32_ubyte1_e32 v7, v221
	v_cvt_f32_ubyte2_e32 v8, v221
	v_cvt_f32_ubyte3_e32 v9, v221
	v_rcp_iflag_f32_e32 v226, v226
	v_rcp_iflag_f32_e32 v227, v227
	v_rcp_iflag_f32_e32 v228, v228
	v_rcp_iflag_f32_e32 v229, v229
	v_rcp_iflag_f32_e32 v230, v230
	v_rcp_iflag_f32_e32 v231, v231
	v_rcp_iflag_f32_e32 v232, v232
	v_rcp_iflag_f32_e32 v233, v233
	s_nop 0
	v_pk_mul_f32 v[2:3], v[226:227], v[2:3]
	v_pk_mul_f32 v[4:5], v[228:229], v[4:5]
	v_pk_mul_f32 v[6:7], v[230:231], v[6:7]
	v_pk_mul_f32 v[8:9], v[232:233], v[8:9]
	v_pk_mul_f32 v[34:35], v[34:35], v[2:3]
	v_pk_mul_f32 v[36:37], v[36:37], v[4:5]
	v_pk_mul_f32 v[30:31], v[30:31], v[6:7]
	v_pk_mul_f32 v[32:33], v[32:33], v[8:9]
	s_waitcnt vmcnt(0)
	v_cvt_f32_ubyte0_e32 v226, v146
	v_cvt_f32_ubyte1_e32 v227, v146
	v_cvt_f32_ubyte2_e32 v228, v146
	v_cvt_f32_ubyte3_e32 v229, v146
	v_cvt_f32_ubyte0_e32 v230, v147
	v_cvt_f32_ubyte1_e32 v231, v147
	v_cvt_f32_ubyte2_e32 v232, v147
	v_cvt_f32_ubyte3_e32 v233, v147
	v_cvt_f32_ubyte0_e32 v2, v222
	v_cvt_f32_ubyte1_e32 v3, v222
	v_cvt_f32_ubyte2_e32 v4, v222
	v_cvt_f32_ubyte3_e32 v5, v222
	v_cvt_f32_ubyte0_e32 v6, v223
	v_cvt_f32_ubyte1_e32 v7, v223
	v_cvt_f32_ubyte2_e32 v8, v223
	v_cvt_f32_ubyte3_e32 v9, v223
	v_rcp_iflag_f32_e32 v226, v226
	v_rcp_iflag_f32_e32 v227, v227
	v_rcp_iflag_f32_e32 v228, v228
	v_rcp_iflag_f32_e32 v229, v229
	v_rcp_iflag_f32_e32 v230, v230
	v_rcp_iflag_f32_e32 v231, v231
	v_rcp_iflag_f32_e32 v232, v232
	v_rcp_iflag_f32_e32 v233, v233
	s_nop 0
	v_pk_mul_f32 v[2:3], v[226:227], v[2:3]
	v_pk_mul_f32 v[4:5], v[228:229], v[4:5]
	v_pk_mul_f32 v[6:7], v[230:231], v[6:7]
	v_pk_mul_f32 v[8:9], v[232:233], v[8:9]
	v_pk_mul_f32 v[26:27], v[26:27], v[2:3]
	v_pk_mul_f32 v[28:29], v[28:29], v[4:5]
	v_pk_mul_f32 v[22:23], v[22:23], v[6:7]
	v_pk_mul_f32 v[24:25], v[24:25], v[8:9]
	v_cvt_f32_ubyte0_e32 v226, v148
	v_cvt_f32_ubyte1_e32 v227, v148
	v_cvt_f32_ubyte2_e32 v228, v148
	v_cvt_f32_ubyte3_e32 v229, v148
	v_cvt_f32_ubyte0_e32 v230, v149
	v_cvt_f32_ubyte1_e32 v231, v149
	v_cvt_f32_ubyte2_e32 v232, v149
	v_cvt_f32_ubyte3_e32 v233, v149
	v_cvt_f32_ubyte0_e32 v2, v224
	v_cvt_f32_ubyte1_e32 v3, v224
	v_cvt_f32_ubyte2_e32 v4, v224
	v_cvt_f32_ubyte3_e32 v5, v224
	v_cvt_f32_ubyte0_e32 v6, v225
	v_cvt_f32_ubyte1_e32 v7, v225
	v_cvt_f32_ubyte2_e32 v8, v225
	v_cvt_f32_ubyte3_e32 v9, v225
	v_rcp_iflag_f32_e32 v226, v226
	v_rcp_iflag_f32_e32 v227, v227
	v_rcp_iflag_f32_e32 v228, v228
	v_rcp_iflag_f32_e32 v229, v229
	v_rcp_iflag_f32_e32 v230, v230
	v_rcp_iflag_f32_e32 v231, v231
	v_rcp_iflag_f32_e32 v232, v232
	v_rcp_iflag_f32_e32 v233, v233
	s_nop 0
	v_pk_mul_f32 v[2:3], v[226:227], v[2:3]
	v_pk_mul_f32 v[4:5], v[228:229], v[4:5]
	v_pk_mul_f32 v[6:7], v[230:231], v[6:7]
	v_pk_mul_f32 v[8:9], v[232:233], v[8:9]
	v_pk_mul_f32 v[18:19], v[18:19], v[2:3]
	v_pk_mul_f32 v[20:21], v[20:21], v[4:5]
	v_pk_mul_f32 v[14:15], v[14:15], v[6:7]
	v_pk_mul_f32 v[16:17], v[16:17], v[8:9]
	s_branch .Lp3c_done
; __device__ __forceinline__ unsigned pk2(float lo, float hi) { f32x2 v = {lo, hi}; bf16x2_t b = __builtin_convertvector(v, bf16x2_t); return __builtin_bit_cast(unsigned, b); }
; __device__ __forceinline__ float frcp(float x) { return __builtin_amdgcn_rcpf(x); }
;     static __device__ __forceinline__ float ub(unsigned w, int i) { return (float)((w >> (8 * i)) & 0xffu); }
;     __device__ __forceinline__ void chain(Acc& acc, const Unit& u, int wr, int wc, int fr, int fq) const {
;     ...
;             for (int m = 0; m < 4; ++m)
; #pragma unroll
;                 for (int bj = 0; bj < 2; ++bj) { const unsigned char* p = GT + (size_t)(row0 + ai * HALF + m * 16) * NGT + col0 + bj * HALF;
;                     g[m][bj] = *(const u32x2*)(p + sub * DM); h[m][bj] = *(const u32x2*)(p + subn * DM); }
; #pragma unroll
;             for (int m = 0; m < 4; ++m)
; #pragma unroll
;                 for (int bj = 0; bj < 2; ++bj) { const u32x2 gg = g[m][bj], hh = h[m][bj];
;                     float sc[8];
;                     if (sub < 2) {
; #pragma unroll
;                         for (int e = 0; e < 8; ++e) sc[e] = ub(e < 4 ? gg.x : gg.y, e & 3) * frcp(ub(e < 4 ? hh.x : hh.y, e & 3));
;                     } else {
; #pragma unroll
;                         for (int e = 0; e < 8; ++e) sc[e] = ub(e < 4 ? gg.x : gg.y, e & 3) * (1.0f / 255.0f);
;                     }
;                     f32x4 a0 = acc[ai][bj][m][0], a1 = acc[ai][bj][m][1];
;                     a0 *= (f32x4){sc[0], sc[1], sc[2], sc[3]}; a1 *= (f32x4){sc[4], sc[5], sc[6], sc[7]};
;                     if (sub < 2) { acc[ai][bj][m][0] = a0; acc[ai][bj][m][1] = a1; }
;                     else { u32x4 w; w.x = pk2(a0[0], a0[1]); w.y = pk2(a0[2], a0[3]); w.z = pk2(a1[0], a1[1]); w.w = pk2(a1[2], a1[3]);
;                         *(u32x4*)(MERGED + (size_t)(row0 + ai * HALF + m * 16) * DM + col0 + bj * HALF) = w; } }
.Lp3c_last:
	global_load_dwordx4 v[190:193], v236, s[40:41]
	global_load_dwordx4 v[194:197], v237, s[40:41]
	global_load_dwordx4 v[198:201], v238, s[40:41]
	global_load_dwordx4 v[202:205], v239, s[40:41]
	global_load_dwordx4 v[210:213], v240, s[40:41]
	global_load_dwordx4 v[214:217], v241, s[40:41]
	global_load_dwordx4 v[218:221], v242, s[40:41]
	global_load_dwordx4 v[222:225], v243, s[40:41]
	v_lshlrev_b32_e32 v235, 1, v235
	v_lshl_add_u32 v244, v234, 12, v235
	v_add_u32_e32 v245, 0x10000, v244
	v_add_u32_e32 v246, 0x20000, v244
	v_add_u32_e32 v247, 0x30000, v244
	v_add_u32_e32 v248, 0x80000, v244
	v_add_u32_e32 v249, 0x90000, v244
	v_add_u32_e32 v250, 0xa0000, v244
	v_add_u32_e32 v251, 0xb0000, v244
	s_waitcnt vmcnt(7)
	v_cvt_f32_ubyte0_e32 v2, v190
	v_cvt_f32_ubyte1_e32 v3, v190
	v_cvt_f32_ubyte2_e32 v4, v190
	v_cvt_f32_ubyte3_e32 v5, v190
	v_cvt_f32_ubyte0_e32 v6, v191
	v_cvt_f32_ubyte1_e32 v7, v191
	v_cvt_f32_ubyte2_e32 v8, v191
	v_cvt_f32_ubyte3_e32 v9, v191
	v_pk_mul_f32 v[2:3], v[2:3], s[22:23] op_sel_hi:[1,0]
	v_pk_mul_f32 v[4:5], v[4:5], s[22:23] op_sel_hi:[1,0]
	v_pk_mul_f32 v[6:7], v[6:7], s[22:23] op_sel_hi:[1,0]
	v_pk_mul_f32 v[8:9], v[8:9], s[22:23] op_sel_hi:[1,0]
	v_pk_mul_f32 v[2:3], v[66:67], v[2:3]
	v_pk_mul_f32 v[4:5], v[68:69], v[4:5]
	v_pk_mul_f32 v[6:7], v[62:63], v[6:7]
	v_pk_mul_f32 v[8:9], v[64:65], v[8:9]
	v_cvt_pk_bf16_f32 v226, v2, v3
	v_cvt_pk_bf16_f32 v227, v4, v5
	v_cvt_pk_bf16_f32 v228, v6, v7
	v_cvt_pk_bf16_f32 v229, v8, v9
	global_store_dwordx4 v244, v[226:229], s[16:17]
	v_cvt_f32_ubyte0_e32 v2, v192
	v_cvt_f32_ubyte1_e32 v3, v192
	v_cvt_f32_ubyte2_e32 v4, v192
	v_cvt_f32_ubyte3_e32 v5, v192
	v_cvt_f32_ubyte0_e32 v6, v193
	v_cvt_f32_ubyte1_e32 v7, v193
	v_cvt_f32_ubyte2_e32 v8, v193
	v_cvt_f32_ubyte3_e32 v9, v193
	v_pk_mul_f32 v[2:3], v[2:3], s[22:23] op_sel_hi:[1,0]
	v_pk_mul_f32 v[4:5], v[4:5], s[22:23] op_sel_hi:[1,0]
	v_pk_mul_f32 v[6:7], v[6:7], s[22:23] op_sel_hi:[1,0]
	v_pk_mul_f32 v[8:9], v[8:9], s[22:23] op_sel_hi:[1,0]
	v_pk_mul_f32 v[2:3], v[170:171], v[2:3]
	v_pk_mul_f32 v[4:5], v[172:173], v[4:5]
	v_pk_mul_f32 v[6:7], v[166:167], v[6:7]
	v_pk_mul_f32 v[8:9], v[168:169], v[8:9]
	v_cvt_pk_bf16_f32 v230, v2, v3
	v_cvt_pk_bf16_f32 v231, v4, v5
	v_cvt_pk_bf16_f32 v232, v6, v7
	v_cvt_pk_bf16_f32 v233, v8, v9
	global_store_dwordx4 v244, v[230:233], s[16:17] offset:256
	s_waitcnt vmcnt(8)
	v_cvt_f32_ubyte0_e32 v2, v194
	v_cvt_f32_ubyte1_e32 v3, v194
	v_cvt_f32_ubyte2_e32 v4, v194
	v_cvt_f32_ubyte3_e32 v5, v194
	v_cvt_f32_ubyte0_e32 v6, v195
	v_cvt_f32_ubyte1_e32 v7, v195
	v_cvt_f32_ubyte2_e32 v8, v195
	v_cvt_f32_ubyte3_e32 v9, v195
	v_pk_mul_f32 v[2:3], v[2:3], s[22:23] op_sel_hi:[1,0]
	v_pk_mul_f32 v[4:5], v[4:5], s[22:23] op_sel_hi:[1,0]
	v_pk_mul_f32 v[6:7], v[6:7], s[22:23] op_sel_hi:[1,0]
	v_pk_mul_f32 v[8:9], v[8:9], s[22:23] op_sel_hi:[1,0]
	v_pk_mul_f32 v[2:3], v[98:99], v[2:3]
	v_pk_mul_f32 v[4:5], v[100:101], v[4:5]
	v_pk_mul_f32 v[6:7], v[94:95], v[6:7]
	v_pk_mul_f32 v[8:9], v[96:97], v[8:9]
	v_cvt_pk_bf16_f32 v226, v2, v3
	v_cvt_pk_bf16_f32 v227, v4, v5
	v_cvt_pk_bf16_f32 v228, v6, v7
	v_cvt_pk_bf16_f32 v229, v8, v9
	global_store_dwordx4 v245, v[226:229], s[16:17]
	v_cvt_f32_ubyte0_e32 v2, v196
	v_cvt_f32_ubyte1_e32 v3, v196
	v_cvt_f32_ubyte2_e32 v4, v196
	v_cvt_f32_ubyte3_e32 v5, v196
	v_cvt_f32_ubyte0_e32 v6, v197
	v_cvt_f32_ubyte1_e32 v7, v197
	v_cvt_f32_ubyte2_e32 v8, v197
	v_cvt_f32_ubyte3_e32 v9, v197
	v_pk_mul_f32 v[2:3], v[2:3], s[22:23] op_sel_hi:[1,0]
	v_pk_mul_f32 v[4:5], v[4:5], s[22:23] op_sel_hi:[1,0]
	v_pk_mul_f32 v[6:7], v[6:7], s[22:23] op_sel_hi:[1,0]
	v_pk_mul_f32 v[8:9], v[8:9], s[22:23] op_sel_hi:[1,0]
	v_pk_mul_f32 v[2:3], v[162:163], v[2:3]
	v_pk_mul_f32 v[4:5], v[164:165], v[4:5]
	v_pk_mul_f32 v[6:7], v[158:159], v[6:7]
	v_pk_mul_f32 v[8:9], v[160:161], v[8:9]
	v_cvt_pk_bf16_f32 v230, v2, v3
	v_cvt_pk_bf16_f32 v231, v4, v5
	v_cvt_pk_bf16_f32 v232, v6, v7
	v_cvt_pk_bf16_f32 v233, v8, v9
	global_store_dwordx4 v245, v[230:233], s[16:17] offset:256
	s_waitcnt vmcnt(9)
	v_cvt_f32_ubyte0_e32 v2, v198
	v_cvt_f32_ubyte1_e32 v3, v198
	v_cvt_f32_ubyte2_e32 v4, v198
	v_cvt_f32_ubyte3_e32 v5, v198
	v_cvt_f32_ubyte0_e32 v6, v199
	v_cvt_f32_ubyte1_e32 v7, v199
	v_cvt_f32_ubyte2_e32 v8, v199
	v_cvt_f32_ubyte3_e32 v9, v199
	v_pk_mul_f32 v[2:3], v[2:3], s[22:23] op_sel_hi:[1,0]
	v_pk_mul_f32 v[4:5], v[4:5], s[22:23] op_sel_hi:[1,0]
	v_pk_mul_f32 v[6:7], v[6:7], s[22:23] op_sel_hi:[1,0]
	v_pk_mul_f32 v[8:9], v[8:9], s[22:23] op_sel_hi:[1,0]
	v_pk_mul_f32 v[2:3], v[130:131], v[2:3]
	v_pk_mul_f32 v[4:5], v[132:133], v[4:5]
	v_pk_mul_f32 v[6:7], v[126:127], v[6:7]
	v_pk_mul_f32 v[8:9], v[128:129], v[8:9]
	v_cvt_pk_bf16_f32 v226, v2, v3
	v_cvt_pk_bf16_f32 v227, v4, v5
	v_cvt_pk_bf16_f32 v228, v6, v7
	v_cvt_pk_bf16_f32 v229, v8, v9
	global_store_dwordx4 v246, v[226:229], s[16:17]
	v_cvt_f32_ubyte0_e32 v2, v200
	v_cvt_f32_ubyte1_e32 v3, v200
	v_cvt_f32_ubyte2_e32 v4, v200
	v_cvt_f32_ubyte3_e32 v5, v200
	v_cvt_f32_ubyte0_e32 v6, v201
	v_cvt_f32_ubyte1_e32 v7, v201
	v_cvt_f32_ubyte2_e32 v8, v201
	v_cvt_f32_ubyte3_e32 v9, v201
	v_pk_mul_f32 v[2:3], v[2:3], s[22:23] op_sel_hi:[1,0]
	v_pk_mul_f32 v[4:5], v[4:5], s[22:23] op_sel_hi:[1,0]
	v_pk_mul_f32 v[6:7], v[6:7], s[22:23] op_sel_hi:[1,0]
	v_pk_mul_f32 v[8:9], v[8:9], s[22:23] op_sel_hi:[1,0]
	v_pk_mul_f32 v[2:3], v[154:155], v[2:3]
	v_pk_mul_f32 v[4:5], v[156:157], v[4:5]
	v_pk_mul_f32 v[6:7], v[150:151], v[6:7]
	v_pk_mul_f32 v[8:9], v[152:153], v[8:9]
	v_cvt_pk_bf16_f32 v230, v2, v3
	v_cvt_pk_bf16_f32 v231, v4, v5
	v_cvt_pk_bf16_f32 v232, v6, v7
	v_cvt_pk_bf16_f32 v233, v8, v9
	global_store_dwordx4 v246, v[230:233], s[16:17] offset:256
	s_waitcnt vmcnt(10)
; __device__ __forceinline__ unsigned pk2(float lo, float hi) { f32x2 v = {lo, hi}; bf16x2_t b = __builtin_convertvector(v, bf16x2_t); return __builtin_bit_cast(unsigned, b); }
;     static __device__ __forceinline__ float ub(unsigned w, int i) { return (float)((w >> (8 * i)) & 0xffu); }
;     __device__ __forceinline__ void chain(Acc& acc, const Unit& u, int wr, int wc, int fr, int fq) const {
;     ...
;                     } else {
; #pragma unroll
;                         for (int e = 0; e < 8; ++e) sc[e] = ub(e < 4 ? gg.x : gg.y, e & 3) * (1.0f / 255.0f);
;                     }
;                     f32x4 a0 = acc[ai][bj][m][0], a1 = acc[ai][bj][m][1];
;                     a0 *= (f32x4){sc[0], sc[1], sc[2], sc[3]}; a1 *= (f32x4){sc[4], sc[5], sc[6], sc[7]};
;                     if (sub < 2) { acc[ai][bj][m][0] = a0; acc[ai][bj][m][1] = a1; }
;                     else { u32x4 w; w.x = pk2(a0[0], a0[1]); w.y = pk2(a0[2], a0[3]); w.z = pk2(a1[0], a1[1]); w.w = pk2(a1[2], a1[3]);
;                         *(u32x4*)(MERGED + (size_t)(row0 + ai * HALF + m * 16) * DM + col0 + bj * HALF) = w; } }
	v_cvt_f32_ubyte0_e32 v2, v202
	v_cvt_f32_ubyte1_e32 v3, v202
	v_cvt_f32_ubyte2_e32 v4, v202
	v_cvt_f32_ubyte3_e32 v5, v202
	v_cvt_f32_ubyte0_e32 v6, v203
	v_cvt_f32_ubyte1_e32 v7, v203
	v_cvt_f32_ubyte2_e32 v8, v203
	v_cvt_f32_ubyte3_e32 v9, v203
	v_pk_mul_f32 v[2:3], v[2:3], s[22:23] op_sel_hi:[1,0]
	v_pk_mul_f32 v[4:5], v[4:5], s[22:23] op_sel_hi:[1,0]
	v_pk_mul_f32 v[6:7], v[6:7], s[22:23] op_sel_hi:[1,0]
	v_pk_mul_f32 v[8:9], v[8:9], s[22:23] op_sel_hi:[1,0]
	v_pk_mul_f32 v[2:3], v[138:139], v[2:3]
	v_pk_mul_f32 v[4:5], v[140:141], v[4:5]
	v_pk_mul_f32 v[6:7], v[134:135], v[6:7]
	v_pk_mul_f32 v[8:9], v[136:137], v[8:9]
	v_cvt_pk_bf16_f32 v226, v2, v3
	v_cvt_pk_bf16_f32 v227, v4, v5
	v_cvt_pk_bf16_f32 v228, v6, v7
	v_cvt_pk_bf16_f32 v229, v8, v9
	global_store_dwordx4 v247, v[226:229], s[16:17]
	v_cvt_f32_ubyte0_e32 v2, v204
	v_cvt_f32_ubyte1_e32 v3, v204
	v_cvt_f32_ubyte2_e32 v4, v204
	v_cvt_f32_ubyte3_e32 v5, v204
	v_cvt_f32_ubyte0_e32 v6, v205
	v_cvt_f32_ubyte1_e32 v7, v205
	v_cvt_f32_ubyte2_e32 v8, v205
	v_cvt_f32_ubyte3_e32 v9, v205
	v_pk_mul_f32 v[2:3], v[2:3], s[22:23] op_sel_hi:[1,0]
	v_pk_mul_f32 v[4:5], v[4:5], s[22:23] op_sel_hi:[1,0]
	v_pk_mul_f32 v[6:7], v[6:7], s[22:23] op_sel_hi:[1,0]
	v_pk_mul_f32 v[8:9], v[8:9], s[22:23] op_sel_hi:[1,0]
	v_pk_mul_f32 v[2:3], v[122:123], v[2:3]
	v_pk_mul_f32 v[4:5], v[124:125], v[4:5]
	v_pk_mul_f32 v[6:7], v[118:119], v[6:7]
	v_pk_mul_f32 v[8:9], v[120:121], v[8:9]
	v_cvt_pk_bf16_f32 v230, v2, v3
	v_cvt_pk_bf16_f32 v231, v4, v5
	v_cvt_pk_bf16_f32 v232, v6, v7
	v_cvt_pk_bf16_f32 v233, v8, v9
	global_store_dwordx4 v247, v[230:233], s[16:17] offset:256
	s_waitcnt vmcnt(11)
	v_cvt_f32_ubyte0_e32 v2, v210
	v_cvt_f32_ubyte1_e32 v3, v210
	v_cvt_f32_ubyte2_e32 v4, v210
	v_cvt_f32_ubyte3_e32 v5, v210
	v_cvt_f32_ubyte0_e32 v6, v211
	v_cvt_f32_ubyte1_e32 v7, v211
	v_cvt_f32_ubyte2_e32 v8, v211
	v_cvt_f32_ubyte3_e32 v9, v211
	v_pk_mul_f32 v[2:3], v[2:3], s[22:23] op_sel_hi:[1,0]
	v_pk_mul_f32 v[4:5], v[4:5], s[22:23] op_sel_hi:[1,0]
	v_pk_mul_f32 v[6:7], v[6:7], s[22:23] op_sel_hi:[1,0]
	v_pk_mul_f32 v[8:9], v[8:9], s[22:23] op_sel_hi:[1,0]
	v_pk_mul_f32 v[2:3], v[106:107], v[2:3]
	v_pk_mul_f32 v[4:5], v[108:109], v[4:5]
	v_pk_mul_f32 v[6:7], v[102:103], v[6:7]
	v_pk_mul_f32 v[8:9], v[104:105], v[8:9]
	v_cvt_pk_bf16_f32 v226, v2, v3
	v_cvt_pk_bf16_f32 v227, v4, v5
	v_cvt_pk_bf16_f32 v228, v6, v7
	v_cvt_pk_bf16_f32 v229, v8, v9
	global_store_dwordx4 v248, v[226:229], s[16:17]
	v_cvt_f32_ubyte0_e32 v2, v212
	v_cvt_f32_ubyte1_e32 v3, v212
	v_cvt_f32_ubyte2_e32 v4, v212
	v_cvt_f32_ubyte3_e32 v5, v212
	v_cvt_f32_ubyte0_e32 v6, v213
	v_cvt_f32_ubyte1_e32 v7, v213
	v_cvt_f32_ubyte2_e32 v8, v213
	v_cvt_f32_ubyte3_e32 v9, v213
	v_pk_mul_f32 v[2:3], v[2:3], s[22:23] op_sel_hi:[1,0]
	v_pk_mul_f32 v[4:5], v[4:5], s[22:23] op_sel_hi:[1,0]
	v_pk_mul_f32 v[6:7], v[6:7], s[22:23] op_sel_hi:[1,0]
	v_pk_mul_f32 v[8:9], v[8:9], s[22:23] op_sel_hi:[1,0]
	v_pk_mul_f32 v[2:3], v[90:91], v[2:3]
	v_pk_mul_f32 v[4:5], v[92:93], v[4:5]
	v_pk_mul_f32 v[6:7], v[86:87], v[6:7]
	v_pk_mul_f32 v[8:9], v[88:89], v[8:9]
	v_cvt_pk_bf16_f32 v230, v2, v3
	v_cvt_pk_bf16_f32 v231, v4, v5
	v_cvt_pk_bf16_f32 v232, v6, v7
	v_cvt_pk_bf16_f32 v233, v8, v9
	global_store_dwordx4 v248, v[230:233], s[16:17] offset:256
	s_waitcnt vmcnt(12)
; __device__ __forceinline__ unsigned pk2(float lo, float hi) { f32x2 v = {lo, hi}; bf16x2_t b = __builtin_convertvector(v, bf16x2_t); return __builtin_bit_cast(unsigned, b); }
;     static __device__ __forceinline__ float ub(unsigned w, int i) { return (float)((w >> (8 * i)) & 0xffu); }
;     __device__ __forceinline__ void chain(Acc& acc, const Unit& u, int wr, int wc, int fr, int fq) const {
;     ...
;                     } else {
; #pragma unroll
;                         for (int e = 0; e < 8; ++e) sc[e] = ub(e < 4 ? gg.x : gg.y, e & 3) * (1.0f / 255.0f);
;                     }
;                     f32x4 a0 = acc[ai][bj][m][0], a1 = acc[ai][bj][m][1];
;                     a0 *= (f32x4){sc[0], sc[1], sc[2], sc[3]}; a1 *= (f32x4){sc[4], sc[5], sc[6], sc[7]};
;                     if (sub < 2) { acc[ai][bj][m][0] = a0; acc[ai][bj][m][1] = a1; }
;                     else { u32x4 w; w.x = pk2(a0[0], a0[1]); w.y = pk2(a0[2], a0[3]); w.z = pk2(a1[0], a1[1]); w.w = pk2(a1[2], a1[3]);
;                         *(u32x4*)(MERGED + (size_t)(row0 + ai * HALF + m * 16) * DM + col0 + bj * HALF) = w; } }
	v_cvt_f32_ubyte0_e32 v2, v214
	v_cvt_f32_ubyte1_e32 v3, v214
	v_cvt_f32_ubyte2_e32 v4, v214
	v_cvt_f32_ubyte3_e32 v5, v214
	v_cvt_f32_ubyte0_e32 v6, v215
	v_cvt_f32_ubyte1_e32 v7, v215
	v_cvt_f32_ubyte2_e32 v8, v215
	v_cvt_f32_ubyte3_e32 v9, v215
	v_pk_mul_f32 v[2:3], v[2:3], s[22:23] op_sel_hi:[1,0]
	v_pk_mul_f32 v[4:5], v[4:5], s[22:23] op_sel_hi:[1,0]
	v_pk_mul_f32 v[6:7], v[6:7], s[22:23] op_sel_hi:[1,0]
	v_pk_mul_f32 v[8:9], v[8:9], s[22:23] op_sel_hi:[1,0]
	v_pk_mul_f32 v[2:3], v[74:75], v[2:3]
	v_pk_mul_f32 v[4:5], v[76:77], v[4:5]
	v_pk_mul_f32 v[6:7], v[70:71], v[6:7]
	v_pk_mul_f32 v[8:9], v[72:73], v[8:9]
	v_cvt_pk_bf16_f32 v226, v2, v3
	v_cvt_pk_bf16_f32 v227, v4, v5
	v_cvt_pk_bf16_f32 v228, v6, v7
	v_cvt_pk_bf16_f32 v229, v8, v9
	global_store_dwordx4 v249, v[226:229], s[16:17]
	v_cvt_f32_ubyte0_e32 v2, v216
	v_cvt_f32_ubyte1_e32 v3, v216
	v_cvt_f32_ubyte2_e32 v4, v216
	v_cvt_f32_ubyte3_e32 v5, v216
	v_cvt_f32_ubyte0_e32 v6, v217
	v_cvt_f32_ubyte1_e32 v7, v217
	v_cvt_f32_ubyte2_e32 v8, v217
	v_cvt_f32_ubyte3_e32 v9, v217
	v_pk_mul_f32 v[2:3], v[2:3], s[22:23] op_sel_hi:[1,0]
	v_pk_mul_f32 v[4:5], v[4:5], s[22:23] op_sel_hi:[1,0]
	v_pk_mul_f32 v[6:7], v[6:7], s[22:23] op_sel_hi:[1,0]
	v_pk_mul_f32 v[8:9], v[8:9], s[22:23] op_sel_hi:[1,0]
	v_pk_mul_f32 v[2:3], v[58:59], v[2:3]
	v_pk_mul_f32 v[4:5], v[60:61], v[4:5]
	v_pk_mul_f32 v[6:7], v[54:55], v[6:7]
	v_pk_mul_f32 v[8:9], v[56:57], v[8:9]
	v_cvt_pk_bf16_f32 v230, v2, v3
	v_cvt_pk_bf16_f32 v231, v4, v5
	v_cvt_pk_bf16_f32 v232, v6, v7
	v_cvt_pk_bf16_f32 v233, v8, v9
	global_store_dwordx4 v249, v[230:233], s[16:17] offset:256
	s_waitcnt vmcnt(13)
	v_cvt_f32_ubyte0_e32 v2, v218
	v_cvt_f32_ubyte1_e32 v3, v218
	v_cvt_f32_ubyte2_e32 v4, v218
	v_cvt_f32_ubyte3_e32 v5, v218
	v_cvt_f32_ubyte0_e32 v6, v219
	v_cvt_f32_ubyte1_e32 v7, v219
	v_cvt_f32_ubyte2_e32 v8, v219
	v_cvt_f32_ubyte3_e32 v9, v219
	v_pk_mul_f32 v[2:3], v[2:3], s[22:23] op_sel_hi:[1,0]
	v_pk_mul_f32 v[4:5], v[4:5], s[22:23] op_sel_hi:[1,0]
	v_pk_mul_f32 v[6:7], v[6:7], s[22:23] op_sel_hi:[1,0]
	v_pk_mul_f32 v[8:9], v[8:9], s[22:23] op_sel_hi:[1,0]
	v_pk_mul_f32 v[2:3], v[42:43], v[2:3]
	v_pk_mul_f32 v[4:5], v[44:45], v[4:5]
	v_pk_mul_f32 v[6:7], v[38:39], v[6:7]
	v_pk_mul_f32 v[8:9], v[40:41], v[8:9]
	v_cvt_pk_bf16_f32 v226, v2, v3
	v_cvt_pk_bf16_f32 v227, v4, v5
	v_cvt_pk_bf16_f32 v228, v6, v7
	v_cvt_pk_bf16_f32 v229, v8, v9
	global_store_dwordx4 v250, v[226:229], s[16:17]
	v_cvt_f32_ubyte0_e32 v2, v220
	v_cvt_f32_ubyte1_e32 v3, v220
	v_cvt_f32_ubyte2_e32 v4, v220
	v_cvt_f32_ubyte3_e32 v5, v220
	v_cvt_f32_ubyte0_e32 v6, v221
	v_cvt_f32_ubyte1_e32 v7, v221
	v_cvt_f32_ubyte2_e32 v8, v221
	v_cvt_f32_ubyte3_e32 v9, v221
	v_pk_mul_f32 v[2:3], v[2:3], s[22:23] op_sel_hi:[1,0]
	v_pk_mul_f32 v[4:5], v[4:5], s[22:23] op_sel_hi:[1,0]
	v_pk_mul_f32 v[6:7], v[6:7], s[22:23] op_sel_hi:[1,0]
	v_pk_mul_f32 v[8:9], v[8:9], s[22:23] op_sel_hi:[1,0]
	v_pk_mul_f32 v[2:3], v[34:35], v[2:3]
	v_pk_mul_f32 v[4:5], v[36:37], v[4:5]
	v_pk_mul_f32 v[6:7], v[30:31], v[6:7]
	v_pk_mul_f32 v[8:9], v[32:33], v[8:9]
	v_cvt_pk_bf16_f32 v230, v2, v3
	v_cvt_pk_bf16_f32 v231, v4, v5
	v_cvt_pk_bf16_f32 v232, v6, v7
	v_cvt_pk_bf16_f32 v233, v8, v9
	global_store_dwordx4 v250, v[230:233], s[16:17] offset:256
	s_waitcnt vmcnt(14)
	v_cvt_f32_ubyte0_e32 v2, v222
	v_cvt_f32_ubyte1_e32 v3, v222
	v_cvt_f32_ubyte2_e32 v4, v222
	v_cvt_f32_ubyte3_e32 v5, v222
	v_cvt_f32_ubyte0_e32 v6, v223
	v_cvt_f32_ubyte1_e32 v7, v223
	v_cvt_f32_ubyte2_e32 v8, v223
	v_cvt_f32_ubyte3_e32 v9, v223
	v_pk_mul_f32 v[2:3], v[2:3], s[22:23] op_sel_hi:[1,0]
	v_pk_mul_f32 v[4:5], v[4:5], s[22:23] op_sel_hi:[1,0]
	v_pk_mul_f32 v[6:7], v[6:7], s[22:23] op_sel_hi:[1,0]
	v_pk_mul_f32 v[8:9], v[8:9], s[22:23] op_sel_hi:[1,0]
	v_pk_mul_f32 v[2:3], v[26:27], v[2:3]
	v_pk_mul_f32 v[4:5], v[28:29], v[4:5]
	v_pk_mul_f32 v[6:7], v[22:23], v[6:7]
	v_pk_mul_f32 v[8:9], v[24:25], v[8:9]
	v_cvt_pk_bf16_f32 v226, v2, v3
	v_cvt_pk_bf16_f32 v227, v4, v5
	v_cvt_pk_bf16_f32 v228, v6, v7
	v_cvt_pk_bf16_f32 v229, v8, v9
	global_store_dwordx4 v251, v[226:229], s[16:17]
	v_cvt_f32_ubyte0_e32 v2, v224
	v_cvt_f32_ubyte1_e32 v3, v224
	v_cvt_f32_ubyte2_e32 v4, v224
	v_cvt_f32_ubyte3_e32 v5, v224
	v_cvt_f32_ubyte0_e32 v6, v225
	v_cvt_f32_ubyte1_e32 v7, v225
	v_cvt_f32_ubyte2_e32 v8, v225
	v_cvt_f32_ubyte3_e32 v9, v225
	v_pk_mul_f32 v[2:3], v[2:3], s[22:23] op_sel_hi:[1,0]
	v_pk_mul_f32 v[4:5], v[4:5], s[22:23] op_sel_hi:[1,0]
	v_pk_mul_f32 v[6:7], v[6:7], s[22:23] op_sel_hi:[1,0]
	v_pk_mul_f32 v[8:9], v[8:9], s[22:23] op_sel_hi:[1,0]
	v_pk_mul_f32 v[2:3], v[18:19], v[2:3]
	v_pk_mul_f32 v[4:5], v[20:21], v[4:5]
	v_pk_mul_f32 v[6:7], v[14:15], v[6:7]
	v_pk_mul_f32 v[8:9], v[16:17], v[8:9]
	v_cvt_pk_bf16_f32 v230, v2, v3
	v_cvt_pk_bf16_f32 v231, v4, v5
	v_cvt_pk_bf16_f32 v232, v6, v7
	v_cvt_pk_bf16_f32 v233, v8, v9
	global_store_dwordx4 v251, v[230:233], s[16:17] offset:256
